# v55 + per-phase s_setprio flips deleted in the five GEMM main loops (A/B of the priority toggling)
# baseline (speedup 1.0000x reference)
.LBB0_328:
	ds_read_b128 v[154:157], v164
	ds_read_b128 v[168:171], v164 offset:1024
	ds_read_b128 v[172:175], v164 offset:2048
	ds_read_b128 v[176:179], v164 offset:3072
	ds_read_b128 v[180:183], v165
	ds_read_b128 v[184:187], v165 offset:1024
	ds_read_b128 v[188:191], v165 offset:2048
	ds_read_b128 v[196:199], v165 offset:3072
	s_add_u32 s44, s42, 0xfffc0080
	s_addc_u32 s45, s43, -1
	s_cmp_eq_u32 s73, 12
	s_cselect_b32 s47, s3, s45
	s_cselect_b32 s46, s8, s44
	s_cselect_b32 s45, s35, s72
	s_cselect_b32 s44, s37, s71
	v_lshl_add_u64 v[192:193], s[42:43], 0, v[146:147]
	s_add_i32 m0, s17, 0xc000
	ds_read_b128 v[204:207], v166
	ds_read_b128 v[208:211], v166 offset:1024
	ds_read_b128 v[212:215], v166 offset:2048
	ds_read_b128 v[216:219], v166 offset:3072
	ds_read_b128 v[220:223], v166 offset:4096
	ds_read_b128 v[224:227], v166 offset:5120
	ds_read_b128 v[228:231], v166 offset:6144
	ds_read_b128 v[232:235], v166 offset:7168
	global_load_lds_dwordx4 v[192:193], off
	v_lshl_add_u64 v[192:193], s[42:43], 0, v[148:149]
	s_add_i32 m0, s17, 0xe000
	s_nop 0
	global_load_lds_dwordx4 v[192:193], off
	s_waitcnt vmcnt(8)
	s_waitcnt lgkmcnt(0)
	s_barrier
	s_waitcnt lgkmcnt(0)
	v_mfma_f32_16x16x32_bf16 v[124:127], v[154:157], v[204:207], v[124:127]
	v_mfma_f32_16x16x32_bf16 v[120:123], v[172:175], v[204:207], v[120:123]
	v_mfma_f32_16x16x32_bf16 v[116:119], v[154:157], v[212:215], v[116:119]
	v_mfma_f32_16x16x32_bf16 v[112:115], v[172:175], v[212:215], v[112:115]
	v_mfma_f32_16x16x32_bf16 v[100:103], v[154:157], v[220:223], v[100:103]
	v_mfma_f32_16x16x32_bf16 v[96:99], v[172:175], v[220:223], v[96:99]
	v_mfma_f32_16x16x32_bf16 v[84:87], v[154:157], v[228:231], v[84:87]
	v_mfma_f32_16x16x32_bf16 v[80:83], v[172:175], v[228:231], v[80:83]
	v_mfma_f32_16x16x32_bf16 v[124:127], v[168:171], v[208:211], v[124:127]
	v_mfma_f32_16x16x32_bf16 v[120:123], v[176:179], v[208:211], v[120:123]
	v_mfma_f32_16x16x32_bf16 v[116:119], v[168:171], v[216:219], v[116:119]
	v_mfma_f32_16x16x32_bf16 v[112:115], v[176:179], v[216:219], v[112:115]
	v_mfma_f32_16x16x32_bf16 v[100:103], v[168:171], v[224:227], v[100:103]
	v_mfma_f32_16x16x32_bf16 v[96:99], v[176:179], v[224:227], v[96:99]
	v_mfma_f32_16x16x32_bf16 v[84:87], v[168:171], v[232:235], v[84:87]
	v_mfma_f32_16x16x32_bf16 v[80:83], v[176:179], v[232:235], v[80:83]
	v_mfma_f32_16x16x32_bf16 v[108:111], v[180:183], v[204:207], v[108:111]
	v_mfma_f32_16x16x32_bf16 v[104:107], v[188:191], v[204:207], v[104:107]
	v_mfma_f32_16x16x32_bf16 v[92:95], v[180:183], v[212:215], v[92:95]
	v_mfma_f32_16x16x32_bf16 v[88:91], v[188:191], v[212:215], v[88:91]
	v_mfma_f32_16x16x32_bf16 v[76:79], v[180:183], v[220:223], v[76:79]
	v_mfma_f32_16x16x32_bf16 v[72:75], v[188:191], v[220:223], v[72:75]
	v_mfma_f32_16x16x32_bf16 v[68:71], v[180:183], v[228:231], v[68:71]
	v_mfma_f32_16x16x32_bf16 v[64:67], v[188:191], v[228:231], v[64:67]
	v_mfma_f32_16x16x32_bf16 v[108:111], v[184:187], v[208:211], v[108:111]
	v_mfma_f32_16x16x32_bf16 v[104:107], v[196:199], v[208:211], v[104:107]
	v_mfma_f32_16x16x32_bf16 v[92:95], v[184:187], v[216:219], v[92:95]
	v_mfma_f32_16x16x32_bf16 v[88:91], v[196:199], v[216:219], v[88:91]
	v_mfma_f32_16x16x32_bf16 v[76:79], v[184:187], v[224:227], v[76:79]
	v_mfma_f32_16x16x32_bf16 v[72:75], v[196:199], v[224:227], v[72:75]
	v_mfma_f32_16x16x32_bf16 v[68:71], v[184:187], v[232:235], v[68:71]
	v_mfma_f32_16x16x32_bf16 v[64:67], v[196:199], v[232:235], v[64:67]
	s_barrier
	s_add_i32 s76, s65, s33
	v_lshl_add_u64 v[192:193], s[44:45], 0, v[132:133]
	s_mov_b32 m0, s76
	ds_read_b128 v[204:207], v166 offset:16384
	ds_read_b128 v[208:211], v166 offset:17408
	ds_read_b128 v[212:215], v166 offset:18432
	ds_read_b128 v[216:219], v166 offset:19456
	ds_read_b128 v[220:223], v166 offset:20480
	ds_read_b128 v[224:227], v166 offset:21504
	ds_read_b128 v[228:231], v166 offset:22528
	ds_read_b128 v[232:235], v166 offset:23552
	global_load_lds_dwordx4 v[192:193], off
	s_add_i32 m0, s76, 0x2000
	s_add_u32 s76, s44, 0x40000
	v_lshl_add_u64 v[200:201], s[44:45], 0, v[136:137]
	s_addc_u32 s77, s45, 0
	s_add_i32 s78, s66, s33
	global_load_lds_dwordx4 v[200:201], off
	v_lshl_add_u64 v[236:237], s[76:77], 0, v[132:133]
	s_mov_b32 m0, s78
	v_lshl_add_u64 v[238:239], s[46:47], 0, v[134:135]
	global_load_lds_dwordx4 v[236:237], off
	v_lshl_add_u64 v[236:237], s[76:77], 0, v[136:137]
	s_add_i32 m0, s78, 0x2000
	s_nop 0
	global_load_lds_dwordx4 v[236:237], off
	v_lshl_add_u64 v[236:237], s[46:47], 0, v[130:131]
	s_mov_b32 m0, s17
	s_nop 0
	global_load_lds_dwordx4 v[236:237], off
	s_mov_b32 m0, s48
	s_nop 0
	global_load_lds_dwordx4 v[238:239], off
	s_waitcnt vmcnt(8)
	s_waitcnt lgkmcnt(0)
	s_barrier
	s_waitcnt lgkmcnt(0)
	v_mfma_f32_16x16x32_bf16 v[60:63], v[154:157], v[204:207], v[60:63]
	v_mfma_f32_16x16x32_bf16 v[56:59], v[172:175], v[204:207], v[56:59]
	v_mfma_f32_16x16x32_bf16 v[52:55], v[154:157], v[212:215], v[52:55]
	v_mfma_f32_16x16x32_bf16 v[48:51], v[172:175], v[212:215], v[48:51]
	v_mfma_f32_16x16x32_bf16 v[36:39], v[154:157], v[220:223], v[36:39]
	v_mfma_f32_16x16x32_bf16 v[32:35], v[172:175], v[220:223], v[32:35]
	v_mfma_f32_16x16x32_bf16 v[20:23], v[154:157], v[228:231], v[20:23]
	v_mfma_f32_16x16x32_bf16 v[16:19], v[172:175], v[228:231], v[16:19]
	v_mfma_f32_16x16x32_bf16 v[60:63], v[168:171], v[208:211], v[60:63]
	v_mfma_f32_16x16x32_bf16 v[56:59], v[176:179], v[208:211], v[56:59]
	v_mfma_f32_16x16x32_bf16 v[52:55], v[168:171], v[216:219], v[52:55]
	v_mfma_f32_16x16x32_bf16 v[48:51], v[176:179], v[216:219], v[48:51]
	v_mfma_f32_16x16x32_bf16 v[36:39], v[168:171], v[224:227], v[36:39]
	v_mfma_f32_16x16x32_bf16 v[32:35], v[176:179], v[224:227], v[32:35]
	v_mfma_f32_16x16x32_bf16 v[20:23], v[168:171], v[232:235], v[20:23]
	v_mfma_f32_16x16x32_bf16 v[16:19], v[176:179], v[232:235], v[16:19]
	v_mfma_f32_16x16x32_bf16 v[44:47], v[180:183], v[204:207], v[44:47]
	v_mfma_f32_16x16x32_bf16 v[40:43], v[188:191], v[204:207], v[40:43]
	v_mfma_f32_16x16x32_bf16 v[28:31], v[180:183], v[212:215], v[28:31]
	v_mfma_f32_16x16x32_bf16 v[24:27], v[188:191], v[212:215], v[24:27]
	v_mfma_f32_16x16x32_bf16 v[12:15], v[180:183], v[220:223], v[12:15]
	v_mfma_f32_16x16x32_bf16 v[8:11], v[188:191], v[220:223], v[8:11]
	v_mfma_f32_16x16x32_bf16 v[4:7], v[180:183], v[228:231], v[4:7]
	v_mfma_f32_16x16x32_bf16 v[0:3], v[188:191], v[228:231], v[0:3]
	v_mfma_f32_16x16x32_bf16 v[44:47], v[184:187], v[208:211], v[44:47]
	v_mfma_f32_16x16x32_bf16 v[40:43], v[196:199], v[208:211], v[40:43]
	v_mfma_f32_16x16x32_bf16 v[28:31], v[184:187], v[216:219], v[28:31]
	v_mfma_f32_16x16x32_bf16 v[24:27], v[196:199], v[216:219], v[24:27]
	v_mfma_f32_16x16x32_bf16 v[12:15], v[184:187], v[224:227], v[12:15]
	v_mfma_f32_16x16x32_bf16 v[8:11], v[196:199], v[224:227], v[8:11]
	v_mfma_f32_16x16x32_bf16 v[4:7], v[184:187], v[232:235], v[4:7]
	v_mfma_f32_16x16x32_bf16 v[0:3], v[196:199], v[232:235], v[0:3]
	s_barrier
	s_add_i32 s76, 0, 0x18000
	v_add_u32_e32 v138, s76, v161
	s_add_i32 s77, 0, 0x1c000
	ds_read_b128 v[154:157], v138
	ds_read_b128 v[168:171], v138 offset:1024
	ds_read_b128 v[172:175], v138 offset:2048
	ds_read_b128 v[176:179], v138 offset:3072
	v_add_u32_e32 v138, s77, v161
	ds_read_b128 v[180:183], v138
	ds_read_b128 v[184:187], v138 offset:1024
	ds_read_b128 v[188:191], v138 offset:2048
	ds_read_b128 v[196:199], v138 offset:3072
	s_add_u32 s46, s46, 0x40000
	s_addc_u32 s47, s47, 0
	s_mov_b32 m0, s49
	v_lshl_add_u64 v[240:241], s[46:47], 0, v[130:131]
	ds_read_b128 v[204:207], v166 offset:32768
	ds_read_b128 v[208:211], v166 offset:33792
	ds_read_b128 v[212:215], v166 offset:34816
	ds_read_b128 v[216:219], v166 offset:35840
	ds_read_b128 v[220:223], v166 offset:36864
	ds_read_b128 v[224:227], v166 offset:37888
	ds_read_b128 v[228:231], v166 offset:38912
	ds_read_b128 v[232:235], v166 offset:39936
	global_load_lds_dwordx4 v[240:241], off
	v_lshl_add_u64 v[240:241], s[46:47], 0, v[134:135]
	s_mov_b32 m0, s53
	s_nop 0
	global_load_lds_dwordx4 v[240:241], off
	s_waitcnt vmcnt(8)
	s_waitcnt lgkmcnt(0)
	s_barrier
	s_waitcnt lgkmcnt(0)
	v_mfma_f32_16x16x32_bf16 v[124:127], v[154:157], v[204:207], v[124:127]
	v_mfma_f32_16x16x32_bf16 v[120:123], v[172:175], v[204:207], v[120:123]
	v_mfma_f32_16x16x32_bf16 v[116:119], v[154:157], v[212:215], v[116:119]
	v_mfma_f32_16x16x32_bf16 v[112:115], v[172:175], v[212:215], v[112:115]
	v_mfma_f32_16x16x32_bf16 v[100:103], v[154:157], v[220:223], v[100:103]
	v_mfma_f32_16x16x32_bf16 v[96:99], v[172:175], v[220:223], v[96:99]
	v_mfma_f32_16x16x32_bf16 v[84:87], v[154:157], v[228:231], v[84:87]
	v_mfma_f32_16x16x32_bf16 v[80:83], v[172:175], v[228:231], v[80:83]
	v_mfma_f32_16x16x32_bf16 v[124:127], v[168:171], v[208:211], v[124:127]
	v_mfma_f32_16x16x32_bf16 v[120:123], v[176:179], v[208:211], v[120:123]
	v_mfma_f32_16x16x32_bf16 v[116:119], v[168:171], v[216:219], v[116:119]
	v_mfma_f32_16x16x32_bf16 v[112:115], v[176:179], v[216:219], v[112:115]
	v_mfma_f32_16x16x32_bf16 v[100:103], v[168:171], v[224:227], v[100:103]
	v_mfma_f32_16x16x32_bf16 v[96:99], v[176:179], v[224:227], v[96:99]
	v_mfma_f32_16x16x32_bf16 v[84:87], v[168:171], v[232:235], v[84:87]
	v_mfma_f32_16x16x32_bf16 v[80:83], v[176:179], v[232:235], v[80:83]
	v_mfma_f32_16x16x32_bf16 v[108:111], v[180:183], v[204:207], v[108:111]
	v_mfma_f32_16x16x32_bf16 v[104:107], v[188:191], v[204:207], v[104:107]
	v_mfma_f32_16x16x32_bf16 v[92:95], v[180:183], v[212:215], v[92:95]
	v_mfma_f32_16x16x32_bf16 v[88:91], v[188:191], v[212:215], v[88:91]
	v_mfma_f32_16x16x32_bf16 v[76:79], v[180:183], v[220:223], v[76:79]
	v_mfma_f32_16x16x32_bf16 v[72:75], v[188:191], v[220:223], v[72:75]
	v_mfma_f32_16x16x32_bf16 v[68:71], v[180:183], v[228:231], v[68:71]
	v_mfma_f32_16x16x32_bf16 v[64:67], v[188:191], v[228:231], v[64:67]
	v_mfma_f32_16x16x32_bf16 v[108:111], v[184:187], v[208:211], v[108:111]
	v_mfma_f32_16x16x32_bf16 v[104:107], v[196:199], v[208:211], v[104:107]
	v_mfma_f32_16x16x32_bf16 v[92:95], v[184:187], v[216:219], v[92:95]
	v_mfma_f32_16x16x32_bf16 v[88:91], v[196:199], v[216:219], v[88:91]
	v_mfma_f32_16x16x32_bf16 v[76:79], v[184:187], v[224:227], v[76:79]
	v_mfma_f32_16x16x32_bf16 v[72:75], v[196:199], v[224:227], v[72:75]
	v_mfma_f32_16x16x32_bf16 v[68:71], v[184:187], v[232:235], v[68:71]
	v_mfma_f32_16x16x32_bf16 v[64:67], v[196:199], v[232:235], v[64:67]
	s_barrier
	s_add_i32 s46, s76, s33
	v_lshl_add_u64 v[192:193], v[192:193], 0, s[14:15]
	s_mov_b32 m0, s46
	ds_read_b128 v[204:207], v166 offset:49152
	ds_read_b128 v[208:211], v166 offset:50176
	ds_read_b128 v[212:215], v166 offset:51200
	ds_read_b128 v[216:219], v166 offset:52224
	ds_read_b128 v[220:223], v166 offset:53248
	ds_read_b128 v[224:227], v166 offset:54272
	ds_read_b128 v[228:231], v166 offset:55296
	ds_read_b128 v[232:235], v166 offset:56320
	global_load_lds_dwordx4 v[192:193], off
	s_add_i32 m0, s46, 0x2000
	s_add_u32 s44, s44, 0x40080
	v_lshl_add_u64 v[192:193], v[200:201], 0, s[14:15]
	s_addc_u32 s45, s45, 0
	s_add_i32 s46, s77, s33
	global_load_lds_dwordx4 v[192:193], off
	v_lshl_add_u64 v[192:193], s[44:45], 0, v[132:133]
	s_mov_b32 m0, s46
	s_nop 0
	global_load_lds_dwordx4 v[192:193], off
	v_lshl_add_u64 v[192:193], s[44:45], 0, v[136:137]
	s_add_i32 m0, s46, 0x2000
	s_nop 0
	global_load_lds_dwordx4 v[192:193], off
	v_lshl_add_u64 v[192:193], v[236:237], 0, s[14:15]
	s_mov_b32 m0, s58
	s_nop 0
	global_load_lds_dwordx4 v[192:193], off
	v_lshl_add_u64 v[192:193], v[238:239], 0, s[14:15]
	s_mov_b32 m0, s59
	s_nop 0
	global_load_lds_dwordx4 v[192:193], off
	s_waitcnt vmcnt(8)
	s_waitcnt lgkmcnt(0)
	s_barrier
	s_waitcnt lgkmcnt(0)
	v_mfma_f32_16x16x32_bf16 v[60:63], v[154:157], v[204:207], v[60:63]
	v_mfma_f32_16x16x32_bf16 v[56:59], v[172:175], v[204:207], v[56:59]
	v_mfma_f32_16x16x32_bf16 v[52:55], v[154:157], v[212:215], v[52:55]
	v_mfma_f32_16x16x32_bf16 v[48:51], v[172:175], v[212:215], v[48:51]
	v_mfma_f32_16x16x32_bf16 v[36:39], v[154:157], v[220:223], v[36:39]
	v_mfma_f32_16x16x32_bf16 v[32:35], v[172:175], v[220:223], v[32:35]
	v_mfma_f32_16x16x32_bf16 v[20:23], v[154:157], v[228:231], v[20:23]
	v_mfma_f32_16x16x32_bf16 v[16:19], v[172:175], v[228:231], v[16:19]
	v_mfma_f32_16x16x32_bf16 v[60:63], v[168:171], v[208:211], v[60:63]
	v_mfma_f32_16x16x32_bf16 v[56:59], v[176:179], v[208:211], v[56:59]
	v_mfma_f32_16x16x32_bf16 v[52:55], v[168:171], v[216:219], v[52:55]
	v_mfma_f32_16x16x32_bf16 v[48:51], v[176:179], v[216:219], v[48:51]
	v_mfma_f32_16x16x32_bf16 v[36:39], v[168:171], v[224:227], v[36:39]
	v_mfma_f32_16x16x32_bf16 v[32:35], v[176:179], v[224:227], v[32:35]
	v_mfma_f32_16x16x32_bf16 v[20:23], v[168:171], v[232:235], v[20:23]
	v_mfma_f32_16x16x32_bf16 v[16:19], v[176:179], v[232:235], v[16:19]
	v_mfma_f32_16x16x32_bf16 v[44:47], v[180:183], v[204:207], v[44:47]
	v_mfma_f32_16x16x32_bf16 v[40:43], v[188:191], v[204:207], v[40:43]
	v_mfma_f32_16x16x32_bf16 v[28:31], v[180:183], v[212:215], v[28:31]
	v_mfma_f32_16x16x32_bf16 v[24:27], v[188:191], v[212:215], v[24:27]
	v_mfma_f32_16x16x32_bf16 v[12:15], v[180:183], v[220:223], v[12:15]
	v_mfma_f32_16x16x32_bf16 v[8:11], v[188:191], v[220:223], v[8:11]
	v_mfma_f32_16x16x32_bf16 v[4:7], v[180:183], v[228:231], v[4:7]
	v_mfma_f32_16x16x32_bf16 v[0:3], v[188:191], v[228:231], v[0:3]
	v_mfma_f32_16x16x32_bf16 v[44:47], v[184:187], v[208:211], v[44:47]
	v_mfma_f32_16x16x32_bf16 v[40:43], v[196:199], v[208:211], v[40:43]
	v_mfma_f32_16x16x32_bf16 v[28:31], v[184:187], v[216:219], v[28:31]
	v_mfma_f32_16x16x32_bf16 v[24:27], v[196:199], v[216:219], v[24:27]
	v_mfma_f32_16x16x32_bf16 v[12:15], v[184:187], v[224:227], v[12:15]
	v_mfma_f32_16x16x32_bf16 v[8:11], v[196:199], v[224:227], v[8:11]
	v_mfma_f32_16x16x32_bf16 v[4:7], v[184:187], v[232:235], v[4:7]
	v_mfma_f32_16x16x32_bf16 v[0:3], v[196:199], v[232:235], v[0:3]
	s_barrier
	s_add_i32 s73, s73, 2
	s_add_u32 s42, s42, 0x100
	s_addc_u32 s43, s43, 0
	s_add_u32 s71, s71, 0x100
	s_addc_u32 s72, s72, 0
	s_cmp_gt_u32 s73, 13
	s_cbranch_scc0 .LBB0_328
	s_and_b64 vcc, exec, s[18:19]
	s_cbranch_vccz .LBB0_331
	s_barrier

.LBB0_820:
	s_add_u32 s34, s28, s30
	s_addc_u32 s35, s29, s31
	s_add_u32 s34, s34, 0x100
	s_addc_u32 s35, s35, 0
	s_add_u32 s61, s58, s30
	s_addc_u32 s62, s59, s31
	s_add_i32 s63, 0, 0x10000
	v_add_u32_e32 v1, s63, v196
	ds_read_b128 v[132:135], v1
	ds_read_b128 v[136:139], v1 offset:1024
	ds_read_b128 v[140:143], v1 offset:2048
	ds_read_b128 v[144:147], v1 offset:3072
	v_add_u32_e32 v1, s55, v196
	ds_read_b128 v[148:151], v1
	ds_read_b128 v[152:155], v1 offset:1024
	ds_read_b128 v[156:159], v1 offset:2048
	ds_read_b128 v[160:163], v1 offset:3072
	s_cmpk_eq_i32 s30, 0xb00
	s_cselect_b32 s37, s1, s35
	s_cselect_b32 s36, s0, s34
	s_cselect_b32 s35, s27, s62
	s_cselect_b32 s34, s26, s61
	v_lshl_add_u64 v[2:3], v[188:189], 0, s[30:31]
	s_add_i32 m0, s39, 0xc000
	ds_read_b128 v[164:167], v198
	ds_read_b128 v[204:207], v198 offset:1024
	ds_read_b128 v[208:211], v198 offset:2048
	ds_read_b128 v[212:215], v198 offset:3072
	ds_read_b128 v[216:219], v198 offset:4096
	ds_read_b128 v[220:223], v198 offset:5120
	ds_read_b128 v[224:227], v198 offset:6144
	ds_read_b128 v[228:231], v198 offset:7168
	global_load_lds_dwordx4 v[2:3], off
	v_lshl_add_u64 v[2:3], v[190:191], 0, s[30:31]
	s_add_i32 m0, s39, 0xe000
	s_nop 0
	global_load_lds_dwordx4 v[2:3], off
	s_waitcnt vmcnt(8)
	s_waitcnt lgkmcnt(0)
	s_barrier
	s_waitcnt lgkmcnt(0)
	v_mfma_f32_16x16x32_bf16 v[128:131], v[132:135], v[164:167], v[128:131]
	v_mfma_f32_16x16x32_bf16 v[124:127], v[140:143], v[164:167], v[124:127]
	v_mfma_f32_16x16x32_bf16 v[120:123], v[132:135], v[208:211], v[120:123]
	v_mfma_f32_16x16x32_bf16 v[108:111], v[140:143], v[208:211], v[108:111]
	v_mfma_f32_16x16x32_bf16 v[96:99], v[132:135], v[216:219], v[96:99]
	v_mfma_f32_16x16x32_bf16 v[92:95], v[140:143], v[216:219], v[92:95]
	v_mfma_f32_16x16x32_bf16 v[80:83], v[132:135], v[224:227], v[80:83]
	v_mfma_f32_16x16x32_bf16 v[76:79], v[140:143], v[224:227], v[76:79]
	v_mfma_f32_16x16x32_bf16 v[128:131], v[136:139], v[204:207], v[128:131]
	v_mfma_f32_16x16x32_bf16 v[124:127], v[144:147], v[204:207], v[124:127]
	v_mfma_f32_16x16x32_bf16 v[120:123], v[136:139], v[212:215], v[120:123]
	v_mfma_f32_16x16x32_bf16 v[108:111], v[144:147], v[212:215], v[108:111]
	v_mfma_f32_16x16x32_bf16 v[96:99], v[136:139], v[220:223], v[96:99]
	v_mfma_f32_16x16x32_bf16 v[92:95], v[144:147], v[220:223], v[92:95]
	v_mfma_f32_16x16x32_bf16 v[80:83], v[136:139], v[228:231], v[80:83]
	v_mfma_f32_16x16x32_bf16 v[76:79], v[144:147], v[228:231], v[76:79]
	v_mfma_f32_16x16x32_bf16 v[116:119], v[148:151], v[164:167], v[116:119]
	v_mfma_f32_16x16x32_bf16 v[112:115], v[156:159], v[164:167], v[112:115]
	v_mfma_f32_16x16x32_bf16 v[104:107], v[148:151], v[208:211], v[104:107]
	v_mfma_f32_16x16x32_bf16 v[100:103], v[156:159], v[208:211], v[100:103]
	v_mfma_f32_16x16x32_bf16 v[88:91], v[148:151], v[216:219], v[88:91]
	v_mfma_f32_16x16x32_bf16 v[84:87], v[156:159], v[216:219], v[84:87]
	v_mfma_f32_16x16x32_bf16 v[72:75], v[148:151], v[224:227], v[72:75]
	v_mfma_f32_16x16x32_bf16 v[68:71], v[156:159], v[224:227], v[68:71]
	v_mfma_f32_16x16x32_bf16 v[116:119], v[152:155], v[204:207], v[116:119]
	v_mfma_f32_16x16x32_bf16 v[112:115], v[160:163], v[204:207], v[112:115]
	v_mfma_f32_16x16x32_bf16 v[104:107], v[152:155], v[212:215], v[104:107]
	v_mfma_f32_16x16x32_bf16 v[100:103], v[160:163], v[212:215], v[100:103]
	v_mfma_f32_16x16x32_bf16 v[88:91], v[152:155], v[220:223], v[88:91]
	v_mfma_f32_16x16x32_bf16 v[84:87], v[160:163], v[220:223], v[84:87]
	v_mfma_f32_16x16x32_bf16 v[72:75], v[152:155], v[228:231], v[72:75]
	v_mfma_f32_16x16x32_bf16 v[68:71], v[160:163], v[228:231], v[68:71]
	s_barrier
	s_add_i32 s61, s63, s38
	v_lshl_add_u64 v[192:193], s[34:35], 0, v[170:171]
	s_mov_b32 m0, s61
	ds_read_b128 v[164:167], v198 offset:16384
	ds_read_b128 v[204:207], v198 offset:17408
	ds_read_b128 v[208:211], v198 offset:18432
	ds_read_b128 v[212:215], v198 offset:19456
	ds_read_b128 v[216:219], v198 offset:20480
	ds_read_b128 v[220:223], v198 offset:21504
	ds_read_b128 v[224:227], v198 offset:22528
	ds_read_b128 v[228:231], v198 offset:23552
	global_load_lds_dwordx4 v[192:193], off
	s_add_i32 m0, s61, 0x2000
	s_add_u32 s62, s34, 0x60000
	v_lshl_add_u64 v[200:201], s[34:35], 0, v[174:175]
	s_addc_u32 s63, s35, 0
	s_add_i32 s61, s55, s38
	global_load_lds_dwordx4 v[200:201], off
	v_lshl_add_u64 v[2:3], s[62:63], 0, v[170:171]
	s_mov_b32 m0, s61
	v_lshl_add_u64 v[232:233], s[36:37], 0, v[168:169]
	global_load_lds_dwordx4 v[2:3], off
	v_lshl_add_u64 v[2:3], s[62:63], 0, v[174:175]
	s_add_i32 m0, s61, 0x2000
	v_lshl_add_u64 v[234:235], s[36:37], 0, v[172:173]
	global_load_lds_dwordx4 v[2:3], off
	s_mov_b32 m0, s39
	s_nop 0
	global_load_lds_dwordx4 v[232:233], off
	s_mov_b32 m0, s40
	s_nop 0
	global_load_lds_dwordx4 v[234:235], off
	s_waitcnt vmcnt(8)
	s_waitcnt lgkmcnt(0)
	s_barrier
	s_waitcnt lgkmcnt(0)
	v_mfma_f32_16x16x32_bf16 v[64:67], v[132:135], v[164:167], v[64:67]
	v_mfma_f32_16x16x32_bf16 v[60:63], v[140:143], v[164:167], v[60:63]
	v_mfma_f32_16x16x32_bf16 v[48:51], v[132:135], v[208:211], v[48:51]
	v_mfma_f32_16x16x32_bf16 v[44:47], v[140:143], v[208:211], v[44:47]
	v_mfma_f32_16x16x32_bf16 v[32:35], v[132:135], v[216:219], v[32:35]
	v_mfma_f32_16x16x32_bf16 v[28:31], v[140:143], v[216:219], v[28:31]
	v_mfma_f32_16x16x32_bf16 v[16:19], v[132:135], v[224:227], v[16:19]
	v_mfma_f32_16x16x32_bf16 v[12:15], v[140:143], v[224:227], v[12:15]
	v_mfma_f32_16x16x32_bf16 v[64:67], v[136:139], v[204:207], v[64:67]
	v_mfma_f32_16x16x32_bf16 v[60:63], v[144:147], v[204:207], v[60:63]
	v_mfma_f32_16x16x32_bf16 v[48:51], v[136:139], v[212:215], v[48:51]
	v_mfma_f32_16x16x32_bf16 v[44:47], v[144:147], v[212:215], v[44:47]
	v_mfma_f32_16x16x32_bf16 v[32:35], v[136:139], v[220:223], v[32:35]
	v_mfma_f32_16x16x32_bf16 v[28:31], v[144:147], v[220:223], v[28:31]
	v_mfma_f32_16x16x32_bf16 v[16:19], v[136:139], v[228:231], v[16:19]
	v_mfma_f32_16x16x32_bf16 v[12:15], v[144:147], v[228:231], v[12:15]
	v_mfma_f32_16x16x32_bf16 v[56:59], v[148:151], v[164:167], v[56:59]
	v_mfma_f32_16x16x32_bf16 v[52:55], v[156:159], v[164:167], v[52:55]
	v_mfma_f32_16x16x32_bf16 v[40:43], v[148:151], v[208:211], v[40:43]
	v_mfma_f32_16x16x32_bf16 v[36:39], v[156:159], v[208:211], v[36:39]
	v_mfma_f32_16x16x32_bf16 v[24:27], v[148:151], v[216:219], v[24:27]
	v_mfma_f32_16x16x32_bf16 v[20:23], v[156:159], v[216:219], v[20:23]
	v_mfma_f32_16x16x32_bf16 v[8:11], v[148:151], v[224:227], v[8:11]
	v_mfma_f32_16x16x32_bf16 v[2:5], v[156:159], v[224:227], v[4:7]
	v_mfma_f32_16x16x32_bf16 v[56:59], v[152:155], v[204:207], v[56:59]
	v_mfma_f32_16x16x32_bf16 v[52:55], v[160:163], v[204:207], v[52:55]
	v_mfma_f32_16x16x32_bf16 v[40:43], v[152:155], v[212:215], v[40:43]
	v_mfma_f32_16x16x32_bf16 v[36:39], v[160:163], v[212:215], v[36:39]
	v_mfma_f32_16x16x32_bf16 v[24:27], v[152:155], v[220:223], v[24:27]
	v_mfma_f32_16x16x32_bf16 v[20:23], v[160:163], v[220:223], v[20:23]
	v_mfma_f32_16x16x32_bf16 v[8:11], v[152:155], v[228:231], v[8:11]
	v_mfma_f32_16x16x32_bf16 v[2:5], v[160:163], v[228:231], v[2:5]
	s_barrier
	s_add_i32 s61, 0, 0x18000
	v_add_u32_e32 v1, s61, v196
	s_add_i32 s62, 0, 0x1c000
	ds_read_b128 v[132:135], v1
	ds_read_b128 v[136:139], v1 offset:1024
	ds_read_b128 v[140:143], v1 offset:2048
	ds_read_b128 v[144:147], v1 offset:3072
	v_add_u32_e32 v1, s62, v196
	ds_read_b128 v[148:151], v1
	ds_read_b128 v[152:155], v1 offset:1024
	ds_read_b128 v[156:159], v1 offset:2048
	ds_read_b128 v[160:163], v1 offset:3072
	s_add_u32 s36, s36, 0x60000
	s_addc_u32 s37, s37, 0
	s_mov_b32 m0, s41
	v_lshl_add_u64 v[6:7], s[36:37], 0, v[168:169]
	ds_read_b128 v[164:167], v198 offset:32768
	ds_read_b128 v[204:207], v198 offset:33792
	ds_read_b128 v[208:211], v198 offset:34816
	ds_read_b128 v[212:215], v198 offset:35840
	ds_read_b128 v[216:219], v198 offset:36864
	ds_read_b128 v[220:223], v198 offset:37888
	ds_read_b128 v[224:227], v198 offset:38912
	ds_read_b128 v[228:231], v198 offset:39936
	global_load_lds_dwordx4 v[6:7], off
	v_lshl_add_u64 v[6:7], s[36:37], 0, v[172:173]
	s_mov_b32 m0, s42
	s_nop 0
	global_load_lds_dwordx4 v[6:7], off
	s_waitcnt vmcnt(8)
	s_waitcnt lgkmcnt(0)
	s_barrier
	s_waitcnt lgkmcnt(0)
	v_mfma_f32_16x16x32_bf16 v[128:131], v[132:135], v[164:167], v[128:131]
	v_mfma_f32_16x16x32_bf16 v[124:127], v[140:143], v[164:167], v[124:127]
	v_mfma_f32_16x16x32_bf16 v[120:123], v[132:135], v[208:211], v[120:123]
	v_mfma_f32_16x16x32_bf16 v[108:111], v[140:143], v[208:211], v[108:111]
	v_mfma_f32_16x16x32_bf16 v[96:99], v[132:135], v[216:219], v[96:99]
	v_mfma_f32_16x16x32_bf16 v[92:95], v[140:143], v[216:219], v[92:95]
	v_mfma_f32_16x16x32_bf16 v[80:83], v[132:135], v[224:227], v[80:83]
	v_mfma_f32_16x16x32_bf16 v[76:79], v[140:143], v[224:227], v[76:79]
	v_mfma_f32_16x16x32_bf16 v[128:131], v[136:139], v[204:207], v[128:131]
	v_mfma_f32_16x16x32_bf16 v[124:127], v[144:147], v[204:207], v[124:127]
	v_mfma_f32_16x16x32_bf16 v[120:123], v[136:139], v[212:215], v[120:123]
	v_mfma_f32_16x16x32_bf16 v[108:111], v[144:147], v[212:215], v[108:111]
	v_mfma_f32_16x16x32_bf16 v[96:99], v[136:139], v[220:223], v[96:99]
	v_mfma_f32_16x16x32_bf16 v[92:95], v[144:147], v[220:223], v[92:95]
	v_mfma_f32_16x16x32_bf16 v[80:83], v[136:139], v[228:231], v[80:83]
	v_mfma_f32_16x16x32_bf16 v[76:79], v[144:147], v[228:231], v[76:79]
	v_mfma_f32_16x16x32_bf16 v[116:119], v[148:151], v[164:167], v[116:119]
	v_mfma_f32_16x16x32_bf16 v[112:115], v[156:159], v[164:167], v[112:115]
	v_mfma_f32_16x16x32_bf16 v[104:107], v[148:151], v[208:211], v[104:107]
	v_mfma_f32_16x16x32_bf16 v[100:103], v[156:159], v[208:211], v[100:103]
	v_mfma_f32_16x16x32_bf16 v[88:91], v[148:151], v[216:219], v[88:91]
	v_mfma_f32_16x16x32_bf16 v[84:87], v[156:159], v[216:219], v[84:87]
	v_mfma_f32_16x16x32_bf16 v[72:75], v[148:151], v[224:227], v[72:75]
	v_mfma_f32_16x16x32_bf16 v[68:71], v[156:159], v[224:227], v[68:71]
	v_mfma_f32_16x16x32_bf16 v[116:119], v[152:155], v[204:207], v[116:119]
	v_mfma_f32_16x16x32_bf16 v[112:115], v[160:163], v[204:207], v[112:115]
	v_mfma_f32_16x16x32_bf16 v[104:107], v[152:155], v[212:215], v[104:107]
	v_mfma_f32_16x16x32_bf16 v[100:103], v[160:163], v[212:215], v[100:103]
	v_mfma_f32_16x16x32_bf16 v[88:91], v[152:155], v[220:223], v[88:91]
	v_mfma_f32_16x16x32_bf16 v[84:87], v[160:163], v[220:223], v[84:87]
	v_mfma_f32_16x16x32_bf16 v[72:75], v[152:155], v[228:231], v[72:75]
	v_mfma_f32_16x16x32_bf16 v[68:71], v[160:163], v[228:231], v[68:71]
	s_barrier
	s_add_i32 s36, s61, s38
	v_lshl_add_u64 v[6:7], v[192:193], 0, s[8:9]
	s_mov_b32 m0, s36
	ds_read_b128 v[164:167], v198 offset:49152
	ds_read_b128 v[204:207], v198 offset:50176
	ds_read_b128 v[208:211], v198 offset:51200
	ds_read_b128 v[212:215], v198 offset:52224
	ds_read_b128 v[216:219], v198 offset:53248
	ds_read_b128 v[220:223], v198 offset:54272
	ds_read_b128 v[224:227], v198 offset:55296
	ds_read_b128 v[228:231], v198 offset:56320
	global_load_lds_dwordx4 v[6:7], off
	s_add_i32 m0, s36, 0x2000
	s_add_u32 s34, s34, 0x60080
	v_lshl_add_u64 v[6:7], v[200:201], 0, s[8:9]
	s_addc_u32 s35, s35, 0
	s_add_i32 s36, s62, s38
	global_load_lds_dwordx4 v[6:7], off
	v_lshl_add_u64 v[6:7], s[34:35], 0, v[170:171]
	s_mov_b32 m0, s36
	s_nop 0
	global_load_lds_dwordx4 v[6:7], off
	v_lshl_add_u64 v[6:7], s[34:35], 0, v[174:175]
	s_add_i32 m0, s36, 0x2000
	s_nop 0
	global_load_lds_dwordx4 v[6:7], off
	v_lshl_add_u64 v[6:7], v[232:233], 0, s[8:9]
	s_mov_b32 m0, s45
	s_nop 0
	global_load_lds_dwordx4 v[6:7], off
	v_lshl_add_u64 v[6:7], v[234:235], 0, s[8:9]
	s_mov_b32 m0, s46
	s_nop 0
	global_load_lds_dwordx4 v[6:7], off
	s_waitcnt vmcnt(8)
	s_waitcnt lgkmcnt(0)
	s_barrier
	s_waitcnt lgkmcnt(0)
	v_mfma_f32_16x16x32_bf16 v[64:67], v[132:135], v[164:167], v[64:67]
	v_mfma_f32_16x16x32_bf16 v[60:63], v[140:143], v[164:167], v[60:63]
	v_mfma_f32_16x16x32_bf16 v[48:51], v[132:135], v[208:211], v[48:51]
	v_mfma_f32_16x16x32_bf16 v[44:47], v[140:143], v[208:211], v[44:47]
	v_mfma_f32_16x16x32_bf16 v[32:35], v[132:135], v[216:219], v[32:35]
	v_mfma_f32_16x16x32_bf16 v[28:31], v[140:143], v[216:219], v[28:31]
	v_mfma_f32_16x16x32_bf16 v[16:19], v[132:135], v[224:227], v[16:19]
	v_mfma_f32_16x16x32_bf16 v[12:15], v[140:143], v[224:227], v[12:15]
	v_mfma_f32_16x16x32_bf16 v[64:67], v[136:139], v[204:207], v[64:67]
	v_mfma_f32_16x16x32_bf16 v[60:63], v[144:147], v[204:207], v[60:63]
	v_mfma_f32_16x16x32_bf16 v[48:51], v[136:139], v[212:215], v[48:51]
	v_mfma_f32_16x16x32_bf16 v[44:47], v[144:147], v[212:215], v[44:47]
	v_mfma_f32_16x16x32_bf16 v[32:35], v[136:139], v[220:223], v[32:35]
	v_mfma_f32_16x16x32_bf16 v[28:31], v[144:147], v[220:223], v[28:31]
	v_mfma_f32_16x16x32_bf16 v[16:19], v[136:139], v[228:231], v[16:19]
	v_mfma_f32_16x16x32_bf16 v[12:15], v[144:147], v[228:231], v[12:15]
	v_mfma_f32_16x16x32_bf16 v[56:59], v[148:151], v[164:167], v[56:59]
	v_mfma_f32_16x16x32_bf16 v[52:55], v[156:159], v[164:167], v[52:55]
	v_mfma_f32_16x16x32_bf16 v[40:43], v[148:151], v[208:211], v[40:43]
	v_mfma_f32_16x16x32_bf16 v[36:39], v[156:159], v[208:211], v[36:39]
	v_mfma_f32_16x16x32_bf16 v[24:27], v[148:151], v[216:219], v[24:27]
	v_mfma_f32_16x16x32_bf16 v[20:23], v[156:159], v[216:219], v[20:23]
	v_mfma_f32_16x16x32_bf16 v[6:9], v[148:151], v[224:227], v[8:11]
	v_mfma_f32_16x16x32_bf16 v[2:5], v[156:159], v[224:227], v[2:5]
	v_mfma_f32_16x16x32_bf16 v[56:59], v[152:155], v[204:207], v[56:59]
	v_mfma_f32_16x16x32_bf16 v[52:55], v[160:163], v[204:207], v[52:55]
	v_mfma_f32_16x16x32_bf16 v[40:43], v[152:155], v[212:215], v[40:43]
	v_mfma_f32_16x16x32_bf16 v[36:39], v[160:163], v[212:215], v[36:39]
	v_mfma_f32_16x16x32_bf16 v[24:27], v[152:155], v[220:223], v[24:27]
	v_mfma_f32_16x16x32_bf16 v[20:23], v[160:163], v[220:223], v[20:23]
	v_mfma_f32_16x16x32_bf16 v[8:11], v[152:155], v[228:231], v[6:9]
	v_mfma_f32_16x16x32_bf16 v[4:7], v[160:163], v[228:231], v[2:5]
	s_barrier
	s_add_i32 s60, s60, 2
	s_add_u32 s30, s30, 0x100
	s_addc_u32 s31, s31, 0
	s_cmp_gt_u32 s60, 21
	s_cbranch_scc1 .LBB0_823

.LBB0_900:
	ds_read_b128 v[128:131], v206
	ds_read_b128 v[132:135], v206 offset:1024
	ds_read_b128 v[136:139], v206 offset:2048
	ds_read_b128 v[140:143], v206 offset:3072
	ds_read_b128 v[144:147], v207
	ds_read_b128 v[148:151], v207 offset:1024
	ds_read_b128 v[152:155], v207 offset:2048
	ds_read_b128 v[156:159], v207 offset:3072
	s_add_u32 s26, s24, 0xfffc0080
	s_addc_u32 s27, s25, -1
	s_cmp_eq_u32 s46, 12
	s_cselect_b32 s29, s15, s27
	s_cselect_b32 s28, s21, s26
	s_cselect_b32 s27, s13, s45
	s_cselect_b32 s26, s43, s44
	v_lshl_add_u64 v[200:201], s[24:25], 0, v[180:181]
	s_add_i32 m0, s23, 0xc000
	ds_read_b128 v[160:163], v208
	ds_read_b128 v[164:167], v208 offset:1024
	ds_read_b128 v[168:171], v208 offset:2048
	ds_read_b128 v[172:175], v208 offset:3072
	ds_read_b128 v[188:191], v208 offset:4096
	ds_read_b128 v[192:195], v208 offset:5120
	ds_read_b128 v[196:199], v208 offset:6144
	ds_read_b128 v[210:213], v208 offset:7168
	global_load_lds_dwordx4 v[200:201], off
	v_lshl_add_u64 v[200:201], s[24:25], 0, v[182:183]
	s_add_i32 m0, s23, 0xe000
	s_nop 0
	global_load_lds_dwordx4 v[200:201], off
	s_waitcnt vmcnt(8)
	s_waitcnt lgkmcnt(0)
	s_barrier
	s_waitcnt lgkmcnt(0)
	v_mfma_f32_16x16x32_bf16 v[124:127], v[128:131], v[160:163], v[124:127]
	v_mfma_f32_16x16x32_bf16 v[120:123], v[136:139], v[160:163], v[120:123]
	v_mfma_f32_16x16x32_bf16 v[108:111], v[128:131], v[168:171], v[108:111]
	v_mfma_f32_16x16x32_bf16 v[104:107], v[136:139], v[168:171], v[104:107]
	v_mfma_f32_16x16x32_bf16 v[92:95], v[128:131], v[188:191], v[92:95]
	v_mfma_f32_16x16x32_bf16 v[88:91], v[136:139], v[188:191], v[88:91]
	v_mfma_f32_16x16x32_bf16 v[76:79], v[128:131], v[196:199], v[76:79]
	v_mfma_f32_16x16x32_bf16 v[72:75], v[136:139], v[196:199], v[72:75]
	v_mfma_f32_16x16x32_bf16 v[124:127], v[132:135], v[164:167], v[124:127]
	v_mfma_f32_16x16x32_bf16 v[120:123], v[140:143], v[164:167], v[120:123]
	v_mfma_f32_16x16x32_bf16 v[108:111], v[132:135], v[172:175], v[108:111]
	v_mfma_f32_16x16x32_bf16 v[104:107], v[140:143], v[172:175], v[104:107]
	v_mfma_f32_16x16x32_bf16 v[92:95], v[132:135], v[192:195], v[92:95]
	v_mfma_f32_16x16x32_bf16 v[88:91], v[140:143], v[192:195], v[88:91]
	v_mfma_f32_16x16x32_bf16 v[76:79], v[132:135], v[210:213], v[76:79]
	v_mfma_f32_16x16x32_bf16 v[72:75], v[140:143], v[210:213], v[72:75]
	v_mfma_f32_16x16x32_bf16 v[116:119], v[144:147], v[160:163], v[116:119]
	v_mfma_f32_16x16x32_bf16 v[112:115], v[152:155], v[160:163], v[112:115]
	v_mfma_f32_16x16x32_bf16 v[100:103], v[144:147], v[168:171], v[100:103]
	v_mfma_f32_16x16x32_bf16 v[96:99], v[152:155], v[168:171], v[96:99]
	v_mfma_f32_16x16x32_bf16 v[84:87], v[144:147], v[188:191], v[84:87]
	v_mfma_f32_16x16x32_bf16 v[80:83], v[152:155], v[188:191], v[80:83]
	v_mfma_f32_16x16x32_bf16 v[68:71], v[144:147], v[196:199], v[68:71]
	v_mfma_f32_16x16x32_bf16 v[64:67], v[152:155], v[196:199], v[64:67]
	v_mfma_f32_16x16x32_bf16 v[116:119], v[148:151], v[164:167], v[116:119]
	v_mfma_f32_16x16x32_bf16 v[112:115], v[156:159], v[164:167], v[112:115]
	v_mfma_f32_16x16x32_bf16 v[100:103], v[148:151], v[172:175], v[100:103]
	v_mfma_f32_16x16x32_bf16 v[96:99], v[156:159], v[172:175], v[96:99]
	v_mfma_f32_16x16x32_bf16 v[84:87], v[148:151], v[192:195], v[84:87]
	v_mfma_f32_16x16x32_bf16 v[80:83], v[156:159], v[192:195], v[80:83]
	v_mfma_f32_16x16x32_bf16 v[68:71], v[148:151], v[210:213], v[68:71]
	v_mfma_f32_16x16x32_bf16 v[64:67], v[156:159], v[210:213], v[64:67]
	s_barrier
	s_add_i32 s47, s41, s30
	v_lshl_add_u64 v[200:201], s[26:27], 0, v[176:177]
	s_mov_b32 m0, s47
	ds_read_b128 v[160:163], v208 offset:16384
	ds_read_b128 v[164:167], v208 offset:17408
	ds_read_b128 v[168:171], v208 offset:18432
	ds_read_b128 v[172:175], v208 offset:19456
	ds_read_b128 v[188:191], v208 offset:20480
	ds_read_b128 v[192:195], v208 offset:21504
	ds_read_b128 v[196:199], v208 offset:22528
	ds_read_b128 v[210:213], v208 offset:23552
	global_load_lds_dwordx4 v[200:201], off
	s_add_i32 m0, s47, 0x2000
	s_add_u32 s48, s26, 0x40000
	v_lshl_add_u64 v[214:215], s[26:27], 0, v[178:179]
	s_addc_u32 s49, s27, 0
	s_add_i32 s47, s42, s30
	global_load_lds_dwordx4 v[214:215], off
	v_lshl_add_u64 v[216:217], s[48:49], 0, v[176:177]
	s_mov_b32 m0, s47
	v_lshl_add_u64 v[218:219], s[28:29], 0, v[178:179]
	global_load_lds_dwordx4 v[216:217], off
	v_lshl_add_u64 v[216:217], s[48:49], 0, v[178:179]
	s_add_i32 m0, s47, 0x2000
	s_nop 0
	global_load_lds_dwordx4 v[216:217], off
	v_lshl_add_u64 v[216:217], s[28:29], 0, v[176:177]
	s_mov_b32 m0, s23
	s_nop 0
	global_load_lds_dwordx4 v[216:217], off
	s_mov_b32 m0, s31
	s_nop 0
	global_load_lds_dwordx4 v[218:219], off
	s_waitcnt vmcnt(8)
	s_waitcnt lgkmcnt(0)
	s_barrier
	s_waitcnt lgkmcnt(0)
	v_mfma_f32_16x16x32_bf16 v[60:63], v[128:131], v[160:163], v[60:63]
	v_mfma_f32_16x16x32_bf16 v[56:59], v[136:139], v[160:163], v[56:59]
	v_mfma_f32_16x16x32_bf16 v[44:47], v[128:131], v[168:171], v[44:47]
	v_mfma_f32_16x16x32_bf16 v[40:43], v[136:139], v[168:171], v[40:43]
	v_mfma_f32_16x16x32_bf16 v[28:31], v[128:131], v[188:191], v[28:31]
	v_mfma_f32_16x16x32_bf16 v[24:27], v[136:139], v[188:191], v[24:27]
	v_mfma_f32_16x16x32_bf16 v[12:15], v[128:131], v[196:199], v[12:15]
	v_mfma_f32_16x16x32_bf16 v[8:11], v[136:139], v[196:199], v[8:11]
	v_mfma_f32_16x16x32_bf16 v[60:63], v[132:135], v[164:167], v[60:63]
	v_mfma_f32_16x16x32_bf16 v[56:59], v[140:143], v[164:167], v[56:59]
	v_mfma_f32_16x16x32_bf16 v[44:47], v[132:135], v[172:175], v[44:47]
	v_mfma_f32_16x16x32_bf16 v[40:43], v[140:143], v[172:175], v[40:43]
	v_mfma_f32_16x16x32_bf16 v[28:31], v[132:135], v[192:195], v[28:31]
	v_mfma_f32_16x16x32_bf16 v[24:27], v[140:143], v[192:195], v[24:27]
	v_mfma_f32_16x16x32_bf16 v[12:15], v[132:135], v[210:213], v[12:15]
	v_mfma_f32_16x16x32_bf16 v[8:11], v[140:143], v[210:213], v[8:11]
	v_mfma_f32_16x16x32_bf16 v[52:55], v[144:147], v[160:163], v[52:55]
	v_mfma_f32_16x16x32_bf16 v[48:51], v[152:155], v[160:163], v[48:51]
	v_mfma_f32_16x16x32_bf16 v[36:39], v[144:147], v[168:171], v[36:39]
	v_mfma_f32_16x16x32_bf16 v[32:35], v[152:155], v[168:171], v[32:35]
	v_mfma_f32_16x16x32_bf16 v[20:23], v[144:147], v[188:191], v[20:23]
	v_mfma_f32_16x16x32_bf16 v[16:19], v[152:155], v[188:191], v[16:19]
	v_mfma_f32_16x16x32_bf16 v[4:7], v[144:147], v[196:199], v[4:7]
	v_mfma_f32_16x16x32_bf16 v[0:3], v[152:155], v[196:199], v[0:3]
	v_mfma_f32_16x16x32_bf16 v[52:55], v[148:151], v[164:167], v[52:55]
	v_mfma_f32_16x16x32_bf16 v[48:51], v[156:159], v[164:167], v[48:51]
	v_mfma_f32_16x16x32_bf16 v[36:39], v[148:151], v[172:175], v[36:39]
	v_mfma_f32_16x16x32_bf16 v[32:35], v[156:159], v[172:175], v[32:35]
	v_mfma_f32_16x16x32_bf16 v[20:23], v[148:151], v[192:195], v[20:23]
	v_mfma_f32_16x16x32_bf16 v[16:19], v[156:159], v[192:195], v[16:19]
	v_mfma_f32_16x16x32_bf16 v[4:7], v[148:151], v[210:213], v[4:7]
	v_mfma_f32_16x16x32_bf16 v[0:3], v[156:159], v[210:213], v[0:3]
	s_barrier
	s_add_i32 s47, 0, 0x18000
	s_add_i32 s48, 0, 0x1c000
	v_add_u32_e32 v140, s47, v204
	v_add_u32_e32 v156, s48, v204
	ds_read_b128 v[128:131], v140
	ds_read_b128 v[132:135], v140 offset:1024
	ds_read_b128 v[136:139], v140 offset:2048
	ds_read_b128 v[140:143], v140 offset:3072
	ds_read_b128 v[144:147], v156
	ds_read_b128 v[148:151], v156 offset:1024
	ds_read_b128 v[152:155], v156 offset:2048
	ds_read_b128 v[156:159], v156 offset:3072
	s_add_u32 s28, s28, 0x40000
	s_addc_u32 s29, s29, 0
	s_mov_b32 m0, s33
	v_lshl_add_u64 v[220:221], s[28:29], 0, v[176:177]
	ds_read_b128 v[160:163], v208 offset:32768
	ds_read_b128 v[164:167], v208 offset:33792
	ds_read_b128 v[168:171], v208 offset:34816
	ds_read_b128 v[172:175], v208 offset:35840
	ds_read_b128 v[188:191], v208 offset:36864
	ds_read_b128 v[192:195], v208 offset:37888
	ds_read_b128 v[196:199], v208 offset:38912
	ds_read_b128 v[210:213], v208 offset:39936
	global_load_lds_dwordx4 v[220:221], off
	v_lshl_add_u64 v[220:221], s[28:29], 0, v[178:179]
	s_mov_b32 m0, s34
	s_nop 0
	global_load_lds_dwordx4 v[220:221], off
	s_waitcnt vmcnt(8)
	s_waitcnt lgkmcnt(0)
	s_barrier
	s_waitcnt lgkmcnt(0)
	v_mfma_f32_16x16x32_bf16 v[124:127], v[128:131], v[160:163], v[124:127]
	v_mfma_f32_16x16x32_bf16 v[120:123], v[136:139], v[160:163], v[120:123]
	v_mfma_f32_16x16x32_bf16 v[108:111], v[128:131], v[168:171], v[108:111]
	v_mfma_f32_16x16x32_bf16 v[104:107], v[136:139], v[168:171], v[104:107]
	v_mfma_f32_16x16x32_bf16 v[92:95], v[128:131], v[188:191], v[92:95]
	v_mfma_f32_16x16x32_bf16 v[88:91], v[136:139], v[188:191], v[88:91]
	v_mfma_f32_16x16x32_bf16 v[76:79], v[128:131], v[196:199], v[76:79]
	v_mfma_f32_16x16x32_bf16 v[72:75], v[136:139], v[196:199], v[72:75]
	v_mfma_f32_16x16x32_bf16 v[124:127], v[132:135], v[164:167], v[124:127]
	v_mfma_f32_16x16x32_bf16 v[120:123], v[140:143], v[164:167], v[120:123]
	v_mfma_f32_16x16x32_bf16 v[108:111], v[132:135], v[172:175], v[108:111]
	v_mfma_f32_16x16x32_bf16 v[104:107], v[140:143], v[172:175], v[104:107]
	v_mfma_f32_16x16x32_bf16 v[92:95], v[132:135], v[192:195], v[92:95]
	v_mfma_f32_16x16x32_bf16 v[88:91], v[140:143], v[192:195], v[88:91]
	v_mfma_f32_16x16x32_bf16 v[76:79], v[132:135], v[210:213], v[76:79]
	v_mfma_f32_16x16x32_bf16 v[72:75], v[140:143], v[210:213], v[72:75]
	v_mfma_f32_16x16x32_bf16 v[116:119], v[144:147], v[160:163], v[116:119]
	v_mfma_f32_16x16x32_bf16 v[112:115], v[152:155], v[160:163], v[112:115]
	v_mfma_f32_16x16x32_bf16 v[100:103], v[144:147], v[168:171], v[100:103]
	v_mfma_f32_16x16x32_bf16 v[96:99], v[152:155], v[168:171], v[96:99]
	v_mfma_f32_16x16x32_bf16 v[84:87], v[144:147], v[188:191], v[84:87]
	v_mfma_f32_16x16x32_bf16 v[80:83], v[152:155], v[188:191], v[80:83]
	v_mfma_f32_16x16x32_bf16 v[68:71], v[144:147], v[196:199], v[68:71]
	v_mfma_f32_16x16x32_bf16 v[64:67], v[152:155], v[196:199], v[64:67]
	v_mfma_f32_16x16x32_bf16 v[116:119], v[148:151], v[164:167], v[116:119]
	v_mfma_f32_16x16x32_bf16 v[112:115], v[156:159], v[164:167], v[112:115]
	v_mfma_f32_16x16x32_bf16 v[100:103], v[148:151], v[172:175], v[100:103]
	v_mfma_f32_16x16x32_bf16 v[96:99], v[156:159], v[172:175], v[96:99]
	v_mfma_f32_16x16x32_bf16 v[84:87], v[148:151], v[192:195], v[84:87]
	v_mfma_f32_16x16x32_bf16 v[80:83], v[156:159], v[192:195], v[80:83]
	v_mfma_f32_16x16x32_bf16 v[68:71], v[148:151], v[210:213], v[68:71]
	v_mfma_f32_16x16x32_bf16 v[64:67], v[156:159], v[210:213], v[64:67]
	s_barrier
	s_add_i32 s28, s47, s30
	v_lshl_add_u64 v[200:201], v[200:201], 0, s[8:9]
	s_mov_b32 m0, s28
	ds_read_b128 v[160:163], v208 offset:49152
	ds_read_b128 v[164:167], v208 offset:50176
	ds_read_b128 v[168:171], v208 offset:51200
	ds_read_b128 v[172:175], v208 offset:52224
	ds_read_b128 v[188:191], v208 offset:53248
	ds_read_b128 v[192:195], v208 offset:54272
	ds_read_b128 v[196:199], v208 offset:55296
	ds_read_b128 v[210:213], v208 offset:56320
	global_load_lds_dwordx4 v[200:201], off
	s_add_i32 m0, s28, 0x2000
	s_add_u32 s26, s26, 0x40080
	v_lshl_add_u64 v[200:201], v[214:215], 0, s[8:9]
	s_addc_u32 s27, s27, 0
	s_add_i32 s28, s48, s30
	global_load_lds_dwordx4 v[200:201], off
	v_lshl_add_u64 v[200:201], s[26:27], 0, v[176:177]
	s_mov_b32 m0, s28
	s_nop 0
	global_load_lds_dwordx4 v[200:201], off
	v_lshl_add_u64 v[200:201], s[26:27], 0, v[178:179]
	s_add_i32 m0, s28, 0x2000
	s_nop 0
	global_load_lds_dwordx4 v[200:201], off
	v_lshl_add_u64 v[200:201], v[216:217], 0, s[8:9]
	s_mov_b32 m0, s36
	s_nop 0
	global_load_lds_dwordx4 v[200:201], off
	v_lshl_add_u64 v[200:201], v[218:219], 0, s[8:9]
	s_mov_b32 m0, s37
	s_nop 0
	global_load_lds_dwordx4 v[200:201], off
	s_waitcnt vmcnt(8)
	s_waitcnt lgkmcnt(0)
	s_barrier
	s_waitcnt lgkmcnt(0)
	v_mfma_f32_16x16x32_bf16 v[60:63], v[128:131], v[160:163], v[60:63]
	v_mfma_f32_16x16x32_bf16 v[56:59], v[136:139], v[160:163], v[56:59]
	v_mfma_f32_16x16x32_bf16 v[44:47], v[128:131], v[168:171], v[44:47]
	v_mfma_f32_16x16x32_bf16 v[40:43], v[136:139], v[168:171], v[40:43]
	v_mfma_f32_16x16x32_bf16 v[28:31], v[128:131], v[188:191], v[28:31]
	v_mfma_f32_16x16x32_bf16 v[24:27], v[136:139], v[188:191], v[24:27]
	v_mfma_f32_16x16x32_bf16 v[12:15], v[128:131], v[196:199], v[12:15]
	v_mfma_f32_16x16x32_bf16 v[8:11], v[136:139], v[196:199], v[8:11]
	v_mfma_f32_16x16x32_bf16 v[60:63], v[132:135], v[164:167], v[60:63]
	v_mfma_f32_16x16x32_bf16 v[56:59], v[140:143], v[164:167], v[56:59]
	v_mfma_f32_16x16x32_bf16 v[44:47], v[132:135], v[172:175], v[44:47]
	v_mfma_f32_16x16x32_bf16 v[40:43], v[140:143], v[172:175], v[40:43]
	v_mfma_f32_16x16x32_bf16 v[28:31], v[132:135], v[192:195], v[28:31]
	v_mfma_f32_16x16x32_bf16 v[24:27], v[140:143], v[192:195], v[24:27]
	v_mfma_f32_16x16x32_bf16 v[12:15], v[132:135], v[210:213], v[12:15]
	v_mfma_f32_16x16x32_bf16 v[8:11], v[140:143], v[210:213], v[8:11]
	v_mfma_f32_16x16x32_bf16 v[52:55], v[144:147], v[160:163], v[52:55]
	v_mfma_f32_16x16x32_bf16 v[48:51], v[152:155], v[160:163], v[48:51]
	v_mfma_f32_16x16x32_bf16 v[36:39], v[144:147], v[168:171], v[36:39]
	v_mfma_f32_16x16x32_bf16 v[32:35], v[152:155], v[168:171], v[32:35]
	v_mfma_f32_16x16x32_bf16 v[20:23], v[144:147], v[188:191], v[20:23]
	v_mfma_f32_16x16x32_bf16 v[16:19], v[152:155], v[188:191], v[16:19]
	v_mfma_f32_16x16x32_bf16 v[4:7], v[144:147], v[196:199], v[4:7]
	v_mfma_f32_16x16x32_bf16 v[0:3], v[152:155], v[196:199], v[0:3]
	v_mfma_f32_16x16x32_bf16 v[52:55], v[148:151], v[164:167], v[52:55]
	v_mfma_f32_16x16x32_bf16 v[48:51], v[156:159], v[164:167], v[48:51]
	v_mfma_f32_16x16x32_bf16 v[36:39], v[148:151], v[172:175], v[36:39]
	v_mfma_f32_16x16x32_bf16 v[32:35], v[156:159], v[172:175], v[32:35]
	v_mfma_f32_16x16x32_bf16 v[20:23], v[148:151], v[192:195], v[20:23]
	v_mfma_f32_16x16x32_bf16 v[16:19], v[156:159], v[192:195], v[16:19]
	v_mfma_f32_16x16x32_bf16 v[4:7], v[148:151], v[210:213], v[4:7]
	v_mfma_f32_16x16x32_bf16 v[0:3], v[156:159], v[210:213], v[0:3]
	s_barrier
	s_add_i32 s46, s46, 2
	s_add_u32 s24, s24, 0x100
	s_addc_u32 s25, s25, 0
	s_add_u32 s44, s44, 0x100
	s_addc_u32 s45, s45, 0
	s_cmp_gt_u32 s46, 13
	s_cbranch_scc0 .LBB0_900
	s_and_b64 vcc, exec, s[10:11]
	s_cbranch_vccz .LBB0_903
	s_barrier

.LBB0_992:
	v_add_u32_e32 v161, s44, v149
	ds_read_b128 v[162:165], v161
	ds_read_b128 v[166:169], v161 offset:1024
	ds_read_b128 v[170:173], v161 offset:2048
	ds_read_b128 v[174:177], v161 offset:3072
	v_add_u32_e32 v161, s45, v149
	ds_read_b128 v[178:181], v161
	ds_read_b128 v[182:185], v161 offset:1024
	ds_read_b128 v[186:189], v161 offset:2048
	ds_read_b128 v[190:193], v161 offset:3072
	s_add_u32 s30, s26, 0xfffc0080
	s_addc_u32 s31, s27, -1
	s_and_b64 s[28:29], s[28:29], exec
	s_cselect_b32 s31, s21, s31
	s_cselect_b32 s30, s51, s30
	s_cselect_b32 s29, s19, s54
	s_cselect_b32 s28, s52, s53
	v_lshl_add_u64 v[228:229], s[26:27], 0, v[136:137]
	s_add_i32 m0, s35, 0xc000
	ds_read_b128 v[194:197], v151
	ds_read_b128 v[198:201], v151 offset:1024
	ds_read_b128 v[204:207], v151 offset:2048
	ds_read_b128 v[208:211], v151 offset:3072
	ds_read_b128 v[212:215], v151 offset:4096
	ds_read_b128 v[216:219], v151 offset:5120
	ds_read_b128 v[220:223], v151 offset:6144
	ds_read_b128 v[224:227], v151 offset:7168
	global_load_lds_dwordx4 v[228:229], off
	v_lshl_add_u64 v[228:229], s[26:27], 0, v[138:139]
	s_add_i32 m0, s35, 0xe000
	s_nop 0
	global_load_lds_dwordx4 v[228:229], off
	s_waitcnt vmcnt(8)
	s_waitcnt lgkmcnt(0)
	s_barrier
	s_waitcnt lgkmcnt(0)
	v_mfma_f32_16x16x32_bf16 v[124:127], v[162:165], v[194:197], v[124:127]
	v_mfma_f32_16x16x32_bf16 v[120:123], v[170:173], v[194:197], v[120:123]
	v_mfma_f32_16x16x32_bf16 v[108:111], v[162:165], v[204:207], v[108:111]
	v_mfma_f32_16x16x32_bf16 v[104:107], v[170:173], v[204:207], v[104:107]
	v_mfma_f32_16x16x32_bf16 v[92:95], v[162:165], v[212:215], v[92:95]
	v_mfma_f32_16x16x32_bf16 v[88:91], v[170:173], v[212:215], v[88:91]
	v_mfma_f32_16x16x32_bf16 v[76:79], v[162:165], v[220:223], v[76:79]
	v_mfma_f32_16x16x32_bf16 v[72:75], v[170:173], v[220:223], v[72:75]
	v_mfma_f32_16x16x32_bf16 v[124:127], v[166:169], v[198:201], v[124:127]
	v_mfma_f32_16x16x32_bf16 v[120:123], v[174:177], v[198:201], v[120:123]
	v_mfma_f32_16x16x32_bf16 v[108:111], v[166:169], v[208:211], v[108:111]
	v_mfma_f32_16x16x32_bf16 v[104:107], v[174:177], v[208:211], v[104:107]
	v_mfma_f32_16x16x32_bf16 v[92:95], v[166:169], v[216:219], v[92:95]
	v_mfma_f32_16x16x32_bf16 v[88:91], v[174:177], v[216:219], v[88:91]
	v_mfma_f32_16x16x32_bf16 v[76:79], v[166:169], v[224:227], v[76:79]
	v_mfma_f32_16x16x32_bf16 v[72:75], v[174:177], v[224:227], v[72:75]
	v_mfma_f32_16x16x32_bf16 v[116:119], v[178:181], v[194:197], v[116:119]
	v_mfma_f32_16x16x32_bf16 v[112:115], v[186:189], v[194:197], v[112:115]
	v_mfma_f32_16x16x32_bf16 v[100:103], v[178:181], v[204:207], v[100:103]
	v_mfma_f32_16x16x32_bf16 v[96:99], v[186:189], v[204:207], v[96:99]
	v_mfma_f32_16x16x32_bf16 v[84:87], v[178:181], v[212:215], v[84:87]
	v_mfma_f32_16x16x32_bf16 v[80:83], v[186:189], v[212:215], v[80:83]
	v_mfma_f32_16x16x32_bf16 v[68:71], v[178:181], v[220:223], v[68:71]
	v_mfma_f32_16x16x32_bf16 v[64:67], v[186:189], v[220:223], v[64:67]
	v_mfma_f32_16x16x32_bf16 v[116:119], v[182:185], v[198:201], v[116:119]
	v_mfma_f32_16x16x32_bf16 v[112:115], v[190:193], v[198:201], v[112:115]
	v_mfma_f32_16x16x32_bf16 v[100:103], v[182:185], v[208:211], v[100:103]
	v_mfma_f32_16x16x32_bf16 v[96:99], v[190:193], v[208:211], v[96:99]
	v_mfma_f32_16x16x32_bf16 v[84:87], v[182:185], v[216:219], v[84:87]
	v_mfma_f32_16x16x32_bf16 v[80:83], v[190:193], v[216:219], v[80:83]
	v_mfma_f32_16x16x32_bf16 v[68:71], v[182:185], v[224:227], v[68:71]
	v_mfma_f32_16x16x32_bf16 v[64:67], v[190:193], v[224:227], v[64:67]
	s_barrier
	s_add_i32 s56, s44, s34
	v_lshl_add_u64 v[228:229], s[28:29], 0, v[130:131]
	s_mov_b32 m0, s56
	ds_read_b128 v[194:197], v151 offset:16384
	ds_read_b128 v[198:201], v151 offset:17408
	ds_read_b128 v[204:207], v151 offset:18432
	ds_read_b128 v[208:211], v151 offset:19456
	ds_read_b128 v[212:215], v151 offset:20480
	ds_read_b128 v[216:219], v151 offset:21504
	ds_read_b128 v[220:223], v151 offset:22528
	ds_read_b128 v[224:227], v151 offset:23552
	global_load_lds_dwordx4 v[228:229], off
	s_add_i32 m0, s56, 0x2000
	s_add_u32 s56, s28, 0x40000
	v_lshl_add_u64 v[230:231], s[28:29], 0, v[134:135]
	s_addc_u32 s57, s29, 0
	s_add_i32 s58, s45, s34
	global_load_lds_dwordx4 v[230:231], off
	v_lshl_add_u64 v[232:233], s[56:57], 0, v[130:131]
	s_mov_b32 m0, s58
	v_lshl_add_u64 v[234:235], s[30:31], 0, v[132:133]
	global_load_lds_dwordx4 v[232:233], off
	v_lshl_add_u64 v[232:233], s[56:57], 0, v[134:135]
	s_add_i32 m0, s58, 0x2000
	s_nop 0
	global_load_lds_dwordx4 v[232:233], off
	v_lshl_add_u64 v[232:233], s[30:31], 0, v[128:129]
	s_mov_b32 m0, s35
	s_nop 0
	global_load_lds_dwordx4 v[232:233], off
	s_mov_b32 m0, s36
	s_nop 0
	global_load_lds_dwordx4 v[234:235], off
	s_waitcnt vmcnt(8)
	s_waitcnt lgkmcnt(0)
	s_barrier
	s_waitcnt lgkmcnt(0)
	v_mfma_f32_16x16x32_bf16 v[60:63], v[162:165], v[194:197], v[60:63]
	v_mfma_f32_16x16x32_bf16 v[56:59], v[170:173], v[194:197], v[56:59]
	v_mfma_f32_16x16x32_bf16 v[44:47], v[162:165], v[204:207], v[44:47]
	v_mfma_f32_16x16x32_bf16 v[40:43], v[170:173], v[204:207], v[40:43]
	v_mfma_f32_16x16x32_bf16 v[28:31], v[162:165], v[212:215], v[28:31]
	v_mfma_f32_16x16x32_bf16 v[24:27], v[170:173], v[212:215], v[24:27]
	v_mfma_f32_16x16x32_bf16 v[12:15], v[162:165], v[220:223], v[12:15]
	v_mfma_f32_16x16x32_bf16 v[8:11], v[170:173], v[220:223], v[8:11]
	v_mfma_f32_16x16x32_bf16 v[60:63], v[166:169], v[198:201], v[60:63]
	v_mfma_f32_16x16x32_bf16 v[56:59], v[174:177], v[198:201], v[56:59]
	v_mfma_f32_16x16x32_bf16 v[44:47], v[166:169], v[208:211], v[44:47]
	v_mfma_f32_16x16x32_bf16 v[40:43], v[174:177], v[208:211], v[40:43]
	v_mfma_f32_16x16x32_bf16 v[28:31], v[166:169], v[216:219], v[28:31]
	v_mfma_f32_16x16x32_bf16 v[24:27], v[174:177], v[216:219], v[24:27]
	v_mfma_f32_16x16x32_bf16 v[12:15], v[166:169], v[224:227], v[12:15]
	v_mfma_f32_16x16x32_bf16 v[8:11], v[174:177], v[224:227], v[8:11]
	v_mfma_f32_16x16x32_bf16 v[52:55], v[178:181], v[194:197], v[52:55]
	v_mfma_f32_16x16x32_bf16 v[48:51], v[186:189], v[194:197], v[48:51]
	v_mfma_f32_16x16x32_bf16 v[36:39], v[178:181], v[204:207], v[36:39]
	v_mfma_f32_16x16x32_bf16 v[32:35], v[186:189], v[204:207], v[32:35]
	v_mfma_f32_16x16x32_bf16 v[20:23], v[178:181], v[212:215], v[20:23]
	v_mfma_f32_16x16x32_bf16 v[16:19], v[186:189], v[212:215], v[16:19]
	v_mfma_f32_16x16x32_bf16 v[4:7], v[178:181], v[220:223], v[4:7]
	v_mfma_f32_16x16x32_bf16 v[0:3], v[186:189], v[220:223], v[0:3]
	v_mfma_f32_16x16x32_bf16 v[52:55], v[182:185], v[198:201], v[52:55]
	v_mfma_f32_16x16x32_bf16 v[48:51], v[190:193], v[198:201], v[48:51]
	v_mfma_f32_16x16x32_bf16 v[36:39], v[182:185], v[208:211], v[36:39]
	v_mfma_f32_16x16x32_bf16 v[32:35], v[190:193], v[208:211], v[32:35]
	v_mfma_f32_16x16x32_bf16 v[20:23], v[182:185], v[216:219], v[20:23]
	v_mfma_f32_16x16x32_bf16 v[16:19], v[190:193], v[216:219], v[16:19]
	v_mfma_f32_16x16x32_bf16 v[4:7], v[182:185], v[224:227], v[4:7]
	v_mfma_f32_16x16x32_bf16 v[0:3], v[190:193], v[224:227], v[0:3]
	s_barrier
	s_add_i32 s56, 0, 0x18000
	v_add_u32_e32 v161, s56, v149
	s_add_i32 s57, 0, 0x1c000
	ds_read_b128 v[162:165], v161
	ds_read_b128 v[166:169], v161 offset:1024
	ds_read_b128 v[170:173], v161 offset:2048
	ds_read_b128 v[174:177], v161 offset:3072
	v_add_u32_e32 v161, s57, v149
	ds_read_b128 v[178:181], v161
	ds_read_b128 v[182:185], v161 offset:1024
	ds_read_b128 v[186:189], v161 offset:2048
	ds_read_b128 v[190:193], v161 offset:3072
	s_add_u32 s30, s30, 0x40000
	s_addc_u32 s31, s31, 0
	s_mov_b32 m0, s37
	v_lshl_add_u64 v[236:237], s[30:31], 0, v[128:129]
	ds_read_b128 v[194:197], v151 offset:32768
	ds_read_b128 v[198:201], v151 offset:33792
	ds_read_b128 v[204:207], v151 offset:34816
	ds_read_b128 v[208:211], v151 offset:35840
	ds_read_b128 v[212:215], v151 offset:36864
	ds_read_b128 v[216:219], v151 offset:37888
	ds_read_b128 v[220:223], v151 offset:38912
	ds_read_b128 v[224:227], v151 offset:39936
	global_load_lds_dwordx4 v[236:237], off
	v_lshl_add_u64 v[236:237], s[30:31], 0, v[132:133]
	s_mov_b32 m0, s38
	s_nop 0
	global_load_lds_dwordx4 v[236:237], off
	s_waitcnt vmcnt(8)
	s_waitcnt lgkmcnt(0)
	s_barrier
	s_waitcnt lgkmcnt(0)
	v_mfma_f32_16x16x32_bf16 v[124:127], v[162:165], v[194:197], v[124:127]
	v_mfma_f32_16x16x32_bf16 v[120:123], v[170:173], v[194:197], v[120:123]
	v_mfma_f32_16x16x32_bf16 v[108:111], v[162:165], v[204:207], v[108:111]
	v_mfma_f32_16x16x32_bf16 v[104:107], v[170:173], v[204:207], v[104:107]
	v_mfma_f32_16x16x32_bf16 v[92:95], v[162:165], v[212:215], v[92:95]
	v_mfma_f32_16x16x32_bf16 v[88:91], v[170:173], v[212:215], v[88:91]
	v_mfma_f32_16x16x32_bf16 v[76:79], v[162:165], v[220:223], v[76:79]
	v_mfma_f32_16x16x32_bf16 v[72:75], v[170:173], v[220:223], v[72:75]
	v_mfma_f32_16x16x32_bf16 v[124:127], v[166:169], v[198:201], v[124:127]
	v_mfma_f32_16x16x32_bf16 v[120:123], v[174:177], v[198:201], v[120:123]
	v_mfma_f32_16x16x32_bf16 v[108:111], v[166:169], v[208:211], v[108:111]
	v_mfma_f32_16x16x32_bf16 v[104:107], v[174:177], v[208:211], v[104:107]
	v_mfma_f32_16x16x32_bf16 v[92:95], v[166:169], v[216:219], v[92:95]
	v_mfma_f32_16x16x32_bf16 v[88:91], v[174:177], v[216:219], v[88:91]
	v_mfma_f32_16x16x32_bf16 v[76:79], v[166:169], v[224:227], v[76:79]
	v_mfma_f32_16x16x32_bf16 v[72:75], v[174:177], v[224:227], v[72:75]
	v_mfma_f32_16x16x32_bf16 v[116:119], v[178:181], v[194:197], v[116:119]
	v_mfma_f32_16x16x32_bf16 v[112:115], v[186:189], v[194:197], v[112:115]
	v_mfma_f32_16x16x32_bf16 v[100:103], v[178:181], v[204:207], v[100:103]
	v_mfma_f32_16x16x32_bf16 v[96:99], v[186:189], v[204:207], v[96:99]
	v_mfma_f32_16x16x32_bf16 v[84:87], v[178:181], v[212:215], v[84:87]
	v_mfma_f32_16x16x32_bf16 v[80:83], v[186:189], v[212:215], v[80:83]
	v_mfma_f32_16x16x32_bf16 v[68:71], v[178:181], v[220:223], v[68:71]
	v_mfma_f32_16x16x32_bf16 v[64:67], v[186:189], v[220:223], v[64:67]
	v_mfma_f32_16x16x32_bf16 v[116:119], v[182:185], v[198:201], v[116:119]
	v_mfma_f32_16x16x32_bf16 v[112:115], v[190:193], v[198:201], v[112:115]
	v_mfma_f32_16x16x32_bf16 v[100:103], v[182:185], v[208:211], v[100:103]
	v_mfma_f32_16x16x32_bf16 v[96:99], v[190:193], v[208:211], v[96:99]
	v_mfma_f32_16x16x32_bf16 v[84:87], v[182:185], v[216:219], v[84:87]
	v_mfma_f32_16x16x32_bf16 v[80:83], v[190:193], v[216:219], v[80:83]
	v_mfma_f32_16x16x32_bf16 v[68:71], v[182:185], v[224:227], v[68:71]
	v_mfma_f32_16x16x32_bf16 v[64:67], v[190:193], v[224:227], v[64:67]
	s_barrier
	s_add_i32 s30, s56, s34
	v_lshl_add_u64 v[228:229], v[228:229], 0, s[6:7]
	s_mov_b32 m0, s30
	ds_read_b128 v[194:197], v151 offset:49152
	ds_read_b128 v[198:201], v151 offset:50176
	ds_read_b128 v[204:207], v151 offset:51200
	ds_read_b128 v[208:211], v151 offset:52224
	ds_read_b128 v[212:215], v151 offset:53248
	ds_read_b128 v[216:219], v151 offset:54272
	ds_read_b128 v[220:223], v151 offset:55296
	ds_read_b128 v[224:227], v151 offset:56320
	global_load_lds_dwordx4 v[228:229], off
	s_add_i32 m0, s30, 0x2000
	s_add_u32 s28, s28, 0x40080
	v_lshl_add_u64 v[228:229], v[230:231], 0, s[6:7]
	s_addc_u32 s29, s29, 0
	s_add_i32 s30, s57, s34
	global_load_lds_dwordx4 v[228:229], off
	v_lshl_add_u64 v[228:229], s[28:29], 0, v[130:131]
	s_mov_b32 m0, s30
	s_nop 0
	global_load_lds_dwordx4 v[228:229], off
	v_lshl_add_u64 v[228:229], s[28:29], 0, v[134:135]
	s_add_i32 m0, s30, 0x2000
	s_nop 0
	global_load_lds_dwordx4 v[228:229], off
	v_lshl_add_u64 v[228:229], v[232:233], 0, s[6:7]
	s_mov_b32 m0, s40
	s_nop 0
	global_load_lds_dwordx4 v[228:229], off
	v_lshl_add_u64 v[228:229], v[234:235], 0, s[6:7]
	s_mov_b32 m0, s41
	s_nop 0
	global_load_lds_dwordx4 v[228:229], off
	s_waitcnt vmcnt(8)
	s_waitcnt lgkmcnt(0)
	s_barrier
	s_waitcnt lgkmcnt(0)
	v_mfma_f32_16x16x32_bf16 v[60:63], v[162:165], v[194:197], v[60:63]
	v_mfma_f32_16x16x32_bf16 v[56:59], v[170:173], v[194:197], v[56:59]
	v_mfma_f32_16x16x32_bf16 v[44:47], v[162:165], v[204:207], v[44:47]
	v_mfma_f32_16x16x32_bf16 v[40:43], v[170:173], v[204:207], v[40:43]
	v_mfma_f32_16x16x32_bf16 v[28:31], v[162:165], v[212:215], v[28:31]
	v_mfma_f32_16x16x32_bf16 v[24:27], v[170:173], v[212:215], v[24:27]
	v_mfma_f32_16x16x32_bf16 v[12:15], v[162:165], v[220:223], v[12:15]
	v_mfma_f32_16x16x32_bf16 v[8:11], v[170:173], v[220:223], v[8:11]
	v_mfma_f32_16x16x32_bf16 v[60:63], v[166:169], v[198:201], v[60:63]
	v_mfma_f32_16x16x32_bf16 v[56:59], v[174:177], v[198:201], v[56:59]
	v_mfma_f32_16x16x32_bf16 v[44:47], v[166:169], v[208:211], v[44:47]
	v_mfma_f32_16x16x32_bf16 v[40:43], v[174:177], v[208:211], v[40:43]
	v_mfma_f32_16x16x32_bf16 v[28:31], v[166:169], v[216:219], v[28:31]
	v_mfma_f32_16x16x32_bf16 v[24:27], v[174:177], v[216:219], v[24:27]
	v_mfma_f32_16x16x32_bf16 v[12:15], v[166:169], v[224:227], v[12:15]
	v_mfma_f32_16x16x32_bf16 v[8:11], v[174:177], v[224:227], v[8:11]
	v_mfma_f32_16x16x32_bf16 v[52:55], v[178:181], v[194:197], v[52:55]
	v_mfma_f32_16x16x32_bf16 v[48:51], v[186:189], v[194:197], v[48:51]
	v_mfma_f32_16x16x32_bf16 v[36:39], v[178:181], v[204:207], v[36:39]
	v_mfma_f32_16x16x32_bf16 v[32:35], v[186:189], v[204:207], v[32:35]
	v_mfma_f32_16x16x32_bf16 v[20:23], v[178:181], v[212:215], v[20:23]
	v_mfma_f32_16x16x32_bf16 v[16:19], v[186:189], v[212:215], v[16:19]
	v_mfma_f32_16x16x32_bf16 v[4:7], v[178:181], v[220:223], v[4:7]
	v_mfma_f32_16x16x32_bf16 v[0:3], v[186:189], v[220:223], v[0:3]
	v_mfma_f32_16x16x32_bf16 v[52:55], v[182:185], v[198:201], v[52:55]
	v_mfma_f32_16x16x32_bf16 v[48:51], v[190:193], v[198:201], v[48:51]
	v_mfma_f32_16x16x32_bf16 v[36:39], v[182:185], v[208:211], v[36:39]
	v_mfma_f32_16x16x32_bf16 v[32:35], v[190:193], v[208:211], v[32:35]
	v_mfma_f32_16x16x32_bf16 v[20:23], v[182:185], v[216:219], v[20:23]
	v_mfma_f32_16x16x32_bf16 v[16:19], v[190:193], v[216:219], v[16:19]
	v_mfma_f32_16x16x32_bf16 v[4:7], v[182:185], v[224:227], v[4:7]
	v_mfma_f32_16x16x32_bf16 v[0:3], v[190:193], v[224:227], v[0:3]
	s_barrier
	s_add_i32 s55, s55, 2
	s_add_u32 s26, s26, 0x100
	s_addc_u32 s27, s27, 0
	s_add_u32 s53, s53, 0x100
	s_addc_u32 s54, s54, 0
	s_cmp_gt_u32 s55, 13
	s_cbranch_scc1 .LBB0_995

.LBB0_1070:
	ds_read_b128 v[140:143], v193
	ds_read_b128 v[144:147], v193 offset:1024
	ds_read_b128 v[148:151], v193 offset:2048
	ds_read_b128 v[152:155], v193 offset:3072
	ds_read_b128 v[156:159], v194
	ds_read_b128 v[160:163], v194 offset:1024
	ds_read_b128 v[164:167], v194 offset:2048
	ds_read_b128 v[168:171], v194 offset:3072
	s_add_u32 s20, s18, 0xfff00080
	s_addc_u32 s21, s19, -1
	s_cmp_eq_u32 s41, 60
	s_cselect_b32 s23, s11, s21
	s_cselect_b32 s22, s37, s20
	s_cselect_b32 s21, s9, s40
	s_cselect_b32 s20, s38, s39
	v_lshl_add_u64 v[188:189], s[18:19], 0, v[132:133]
	s_add_i32 m0, s17, 0xc000
	ds_read_b128 v[172:175], v195
	ds_read_b128 v[176:179], v195 offset:1024
	ds_read_b128 v[180:183], v195 offset:2048
	ds_read_b128 v[184:187], v195 offset:3072
	ds_read_b128 v[196:199], v195 offset:4096
	ds_read_b128 v[200:203], v195 offset:5120
	ds_read_b128 v[204:207], v195 offset:6144
	ds_read_b128 v[208:211], v195 offset:7168
	global_load_lds_dwordx4 v[188:189], off
	v_lshl_add_u64 v[188:189], s[18:19], 0, v[134:135]
	s_add_i32 m0, s17, 0xe000
	s_nop 0
	global_load_lds_dwordx4 v[188:189], off
	s_waitcnt vmcnt(8)
	s_waitcnt lgkmcnt(0)
	s_barrier
	s_waitcnt lgkmcnt(0)
	v_mfma_f32_16x16x32_bf16 v[124:127], v[140:143], v[172:175], v[124:127]
	v_mfma_f32_16x16x32_bf16 v[120:123], v[148:151], v[172:175], v[120:123]
	v_mfma_f32_16x16x32_bf16 v[112:115], v[140:143], v[180:183], v[112:115]
	v_mfma_f32_16x16x32_bf16 v[104:107], v[148:151], v[180:183], v[104:107]
	v_mfma_f32_16x16x32_bf16 v[96:99], v[140:143], v[196:199], v[96:99]
	v_mfma_f32_16x16x32_bf16 v[88:91], v[148:151], v[196:199], v[88:91]
	v_mfma_f32_16x16x32_bf16 v[80:83], v[140:143], v[204:207], v[80:83]
	v_mfma_f32_16x16x32_bf16 v[72:75], v[148:151], v[204:207], v[72:75]
	v_mfma_f32_16x16x32_bf16 v[124:127], v[144:147], v[176:179], v[124:127]
	v_mfma_f32_16x16x32_bf16 v[120:123], v[152:155], v[176:179], v[120:123]
	v_mfma_f32_16x16x32_bf16 v[112:115], v[144:147], v[184:187], v[112:115]
	v_mfma_f32_16x16x32_bf16 v[104:107], v[152:155], v[184:187], v[104:107]
	v_mfma_f32_16x16x32_bf16 v[96:99], v[144:147], v[200:203], v[96:99]
	v_mfma_f32_16x16x32_bf16 v[88:91], v[152:155], v[200:203], v[88:91]
	v_mfma_f32_16x16x32_bf16 v[80:83], v[144:147], v[208:211], v[80:83]
	v_mfma_f32_16x16x32_bf16 v[72:75], v[152:155], v[208:211], v[72:75]
	v_mfma_f32_16x16x32_bf16 v[116:119], v[156:159], v[172:175], v[116:119]
	v_mfma_f32_16x16x32_bf16 v[108:111], v[164:167], v[172:175], v[108:111]
	v_mfma_f32_16x16x32_bf16 v[100:103], v[156:159], v[180:183], v[100:103]
	v_mfma_f32_16x16x32_bf16 v[92:95], v[164:167], v[180:183], v[92:95]
	v_mfma_f32_16x16x32_bf16 v[84:87], v[156:159], v[196:199], v[84:87]
	v_mfma_f32_16x16x32_bf16 v[76:79], v[164:167], v[196:199], v[76:79]
	v_mfma_f32_16x16x32_bf16 v[68:71], v[156:159], v[204:207], v[68:71]
	v_mfma_f32_16x16x32_bf16 v[64:67], v[164:167], v[204:207], v[64:67]
	v_mfma_f32_16x16x32_bf16 v[116:119], v[160:163], v[176:179], v[116:119]
	v_mfma_f32_16x16x32_bf16 v[108:111], v[168:171], v[176:179], v[108:111]
	v_mfma_f32_16x16x32_bf16 v[100:103], v[160:163], v[184:187], v[100:103]
	v_mfma_f32_16x16x32_bf16 v[92:95], v[168:171], v[184:187], v[92:95]
	v_mfma_f32_16x16x32_bf16 v[84:87], v[160:163], v[200:203], v[84:87]
	v_mfma_f32_16x16x32_bf16 v[76:79], v[168:171], v[200:203], v[76:79]
	v_mfma_f32_16x16x32_bf16 v[68:71], v[160:163], v[208:211], v[68:71]
	v_mfma_f32_16x16x32_bf16 v[64:67], v[168:171], v[208:211], v[64:67]
	s_barrier
	s_add_i32 s42, s34, s25
	v_lshl_add_u64 v[188:189], s[20:21], 0, v[128:129]
	s_mov_b32 m0, s42
	ds_read_b128 v[172:175], v195 offset:16384
	ds_read_b128 v[176:179], v195 offset:17408
	ds_read_b128 v[180:183], v195 offset:18432
	ds_read_b128 v[184:187], v195 offset:19456
	ds_read_b128 v[196:199], v195 offset:20480
	ds_read_b128 v[200:203], v195 offset:21504
	ds_read_b128 v[204:207], v195 offset:22528
	ds_read_b128 v[208:211], v195 offset:23552
	global_load_lds_dwordx4 v[188:189], off
	s_add_i32 m0, s42, 0x2000
	s_add_u32 s42, s20, 0x100000
	v_lshl_add_u64 v[212:213], s[20:21], 0, v[130:131]
	s_addc_u32 s43, s21, 0
	s_add_i32 s44, s35, s25
	global_load_lds_dwordx4 v[212:213], off
	v_lshl_add_u64 v[214:215], s[42:43], 0, v[128:129]
	s_mov_b32 m0, s44
	v_lshl_add_u64 v[216:217], s[22:23], 0, v[130:131]
	global_load_lds_dwordx4 v[214:215], off
	v_lshl_add_u64 v[214:215], s[42:43], 0, v[130:131]
	s_add_i32 m0, s44, 0x2000
	s_nop 0
	global_load_lds_dwordx4 v[214:215], off
	v_lshl_add_u64 v[214:215], s[22:23], 0, v[128:129]
	s_mov_b32 m0, s17
	s_nop 0
	global_load_lds_dwordx4 v[214:215], off
	s_mov_b32 m0, s26
	s_nop 0
	global_load_lds_dwordx4 v[216:217], off
	s_waitcnt vmcnt(8)
	s_waitcnt lgkmcnt(0)
	s_barrier
	s_waitcnt lgkmcnt(0)
	v_mfma_f32_16x16x32_bf16 v[60:63], v[140:143], v[172:175], v[60:63]
	v_mfma_f32_16x16x32_bf16 v[56:59], v[148:151], v[172:175], v[56:59]
	v_mfma_f32_16x16x32_bf16 v[48:51], v[140:143], v[180:183], v[48:51]
	v_mfma_f32_16x16x32_bf16 v[40:43], v[148:151], v[180:183], v[40:43]
	v_mfma_f32_16x16x32_bf16 v[32:35], v[140:143], v[196:199], v[32:35]
	v_mfma_f32_16x16x32_bf16 v[24:27], v[148:151], v[196:199], v[24:27]
	v_mfma_f32_16x16x32_bf16 v[16:19], v[140:143], v[204:207], v[16:19]
	v_mfma_f32_16x16x32_bf16 v[8:11], v[148:151], v[204:207], v[8:11]
	v_mfma_f32_16x16x32_bf16 v[60:63], v[144:147], v[176:179], v[60:63]
	v_mfma_f32_16x16x32_bf16 v[56:59], v[152:155], v[176:179], v[56:59]
	v_mfma_f32_16x16x32_bf16 v[48:51], v[144:147], v[184:187], v[48:51]
	v_mfma_f32_16x16x32_bf16 v[40:43], v[152:155], v[184:187], v[40:43]
	v_mfma_f32_16x16x32_bf16 v[32:35], v[144:147], v[200:203], v[32:35]
	v_mfma_f32_16x16x32_bf16 v[24:27], v[152:155], v[200:203], v[24:27]
	v_mfma_f32_16x16x32_bf16 v[16:19], v[144:147], v[208:211], v[16:19]
	v_mfma_f32_16x16x32_bf16 v[8:11], v[152:155], v[208:211], v[8:11]
	v_mfma_f32_16x16x32_bf16 v[52:55], v[156:159], v[172:175], v[52:55]
	v_mfma_f32_16x16x32_bf16 v[44:47], v[164:167], v[172:175], v[44:47]
	v_mfma_f32_16x16x32_bf16 v[36:39], v[156:159], v[180:183], v[36:39]
	v_mfma_f32_16x16x32_bf16 v[28:31], v[164:167], v[180:183], v[28:31]
	v_mfma_f32_16x16x32_bf16 v[20:23], v[156:159], v[196:199], v[20:23]
	v_mfma_f32_16x16x32_bf16 v[12:15], v[164:167], v[196:199], v[12:15]
	v_mfma_f32_16x16x32_bf16 v[4:7], v[156:159], v[204:207], v[4:7]
	v_mfma_f32_16x16x32_bf16 v[0:3], v[164:167], v[204:207], v[0:3]
	v_mfma_f32_16x16x32_bf16 v[52:55], v[160:163], v[176:179], v[52:55]
	v_mfma_f32_16x16x32_bf16 v[44:47], v[168:171], v[176:179], v[44:47]
	v_mfma_f32_16x16x32_bf16 v[36:39], v[160:163], v[184:187], v[36:39]
	v_mfma_f32_16x16x32_bf16 v[28:31], v[168:171], v[184:187], v[28:31]
	v_mfma_f32_16x16x32_bf16 v[20:23], v[160:163], v[200:203], v[20:23]
	v_mfma_f32_16x16x32_bf16 v[12:15], v[168:171], v[200:203], v[12:15]
	v_mfma_f32_16x16x32_bf16 v[4:7], v[160:163], v[208:211], v[4:7]
	v_mfma_f32_16x16x32_bf16 v[0:3], v[168:171], v[208:211], v[0:3]
	s_barrier
	s_add_i32 s42, 0, 0x18000
	s_add_i32 s43, 0, 0x1c000
	v_add_u32_e32 v152, s42, v191
	v_add_u32_e32 v168, s43, v191
	ds_read_b128 v[140:143], v152
	ds_read_b128 v[144:147], v152 offset:1024
	ds_read_b128 v[148:151], v152 offset:2048
	ds_read_b128 v[152:155], v152 offset:3072
	ds_read_b128 v[156:159], v168
	ds_read_b128 v[160:163], v168 offset:1024
	ds_read_b128 v[164:167], v168 offset:2048
	ds_read_b128 v[168:171], v168 offset:3072
	s_add_u32 s22, s22, 0x100000
	s_addc_u32 s23, s23, 0
	s_mov_b32 m0, s27
	v_lshl_add_u64 v[218:219], s[22:23], 0, v[128:129]
	ds_read_b128 v[172:175], v195 offset:32768
	ds_read_b128 v[176:179], v195 offset:33792
	ds_read_b128 v[180:183], v195 offset:34816
	ds_read_b128 v[184:187], v195 offset:35840
	ds_read_b128 v[196:199], v195 offset:36864
	ds_read_b128 v[200:203], v195 offset:37888
	ds_read_b128 v[204:207], v195 offset:38912
	ds_read_b128 v[208:211], v195 offset:39936
	global_load_lds_dwordx4 v[218:219], off
	v_lshl_add_u64 v[218:219], s[22:23], 0, v[130:131]
	s_mov_b32 m0, s28
	s_nop 0
	global_load_lds_dwordx4 v[218:219], off
	s_waitcnt vmcnt(8)
	s_waitcnt lgkmcnt(0)
	s_barrier
	s_waitcnt lgkmcnt(0)
	v_mfma_f32_16x16x32_bf16 v[124:127], v[140:143], v[172:175], v[124:127]
	v_mfma_f32_16x16x32_bf16 v[120:123], v[148:151], v[172:175], v[120:123]
	v_mfma_f32_16x16x32_bf16 v[112:115], v[140:143], v[180:183], v[112:115]
	v_mfma_f32_16x16x32_bf16 v[104:107], v[148:151], v[180:183], v[104:107]
	v_mfma_f32_16x16x32_bf16 v[96:99], v[140:143], v[196:199], v[96:99]
	v_mfma_f32_16x16x32_bf16 v[88:91], v[148:151], v[196:199], v[88:91]
	v_mfma_f32_16x16x32_bf16 v[80:83], v[140:143], v[204:207], v[80:83]
	v_mfma_f32_16x16x32_bf16 v[72:75], v[148:151], v[204:207], v[72:75]
	v_mfma_f32_16x16x32_bf16 v[124:127], v[144:147], v[176:179], v[124:127]
	v_mfma_f32_16x16x32_bf16 v[120:123], v[152:155], v[176:179], v[120:123]
	v_mfma_f32_16x16x32_bf16 v[112:115], v[144:147], v[184:187], v[112:115]
	v_mfma_f32_16x16x32_bf16 v[104:107], v[152:155], v[184:187], v[104:107]
	v_mfma_f32_16x16x32_bf16 v[96:99], v[144:147], v[200:203], v[96:99]
	v_mfma_f32_16x16x32_bf16 v[88:91], v[152:155], v[200:203], v[88:91]
	v_mfma_f32_16x16x32_bf16 v[80:83], v[144:147], v[208:211], v[80:83]
	v_mfma_f32_16x16x32_bf16 v[72:75], v[152:155], v[208:211], v[72:75]
	v_mfma_f32_16x16x32_bf16 v[116:119], v[156:159], v[172:175], v[116:119]
	v_mfma_f32_16x16x32_bf16 v[108:111], v[164:167], v[172:175], v[108:111]
	v_mfma_f32_16x16x32_bf16 v[100:103], v[156:159], v[180:183], v[100:103]
	v_mfma_f32_16x16x32_bf16 v[92:95], v[164:167], v[180:183], v[92:95]
	v_mfma_f32_16x16x32_bf16 v[84:87], v[156:159], v[196:199], v[84:87]
	v_mfma_f32_16x16x32_bf16 v[76:79], v[164:167], v[196:199], v[76:79]
	v_mfma_f32_16x16x32_bf16 v[68:71], v[156:159], v[204:207], v[68:71]
	v_mfma_f32_16x16x32_bf16 v[64:67], v[164:167], v[204:207], v[64:67]
	v_mfma_f32_16x16x32_bf16 v[116:119], v[160:163], v[176:179], v[116:119]
	v_mfma_f32_16x16x32_bf16 v[108:111], v[168:171], v[176:179], v[108:111]
	v_mfma_f32_16x16x32_bf16 v[100:103], v[160:163], v[184:187], v[100:103]
	v_mfma_f32_16x16x32_bf16 v[92:95], v[168:171], v[184:187], v[92:95]
	v_mfma_f32_16x16x32_bf16 v[84:87], v[160:163], v[200:203], v[84:87]
	v_mfma_f32_16x16x32_bf16 v[76:79], v[168:171], v[200:203], v[76:79]
	v_mfma_f32_16x16x32_bf16 v[68:71], v[160:163], v[208:211], v[68:71]
	v_mfma_f32_16x16x32_bf16 v[64:67], v[168:171], v[208:211], v[64:67]
	s_barrier
	s_add_i32 s22, s42, s25
	v_lshl_add_u64 v[188:189], v[188:189], 0, s[4:5]
	s_mov_b32 m0, s22
	ds_read_b128 v[172:175], v195 offset:49152
	ds_read_b128 v[176:179], v195 offset:50176
	ds_read_b128 v[180:183], v195 offset:51200
	ds_read_b128 v[184:187], v195 offset:52224
	ds_read_b128 v[196:199], v195 offset:53248
	ds_read_b128 v[200:203], v195 offset:54272
	ds_read_b128 v[204:207], v195 offset:55296
	ds_read_b128 v[208:211], v195 offset:56320
	global_load_lds_dwordx4 v[188:189], off
	s_add_i32 m0, s22, 0x2000
	s_add_u32 s20, s20, 0x100080
	v_lshl_add_u64 v[188:189], v[212:213], 0, s[4:5]
	s_addc_u32 s21, s21, 0
	s_add_i32 s22, s43, s25
	global_load_lds_dwordx4 v[188:189], off
	v_lshl_add_u64 v[188:189], s[20:21], 0, v[128:129]
	s_mov_b32 m0, s22
	s_nop 0
	global_load_lds_dwordx4 v[188:189], off
	v_lshl_add_u64 v[188:189], s[20:21], 0, v[130:131]
	s_add_i32 m0, s22, 0x2000
	s_nop 0
	global_load_lds_dwordx4 v[188:189], off
	v_lshl_add_u64 v[188:189], v[214:215], 0, s[4:5]
	s_mov_b32 m0, s30
	s_nop 0
	global_load_lds_dwordx4 v[188:189], off
	v_lshl_add_u64 v[188:189], v[216:217], 0, s[4:5]
	s_mov_b32 m0, s31
	s_nop 0
	global_load_lds_dwordx4 v[188:189], off
	s_waitcnt vmcnt(8)
	s_waitcnt lgkmcnt(0)
	s_barrier
	s_waitcnt lgkmcnt(0)
	v_mfma_f32_16x16x32_bf16 v[60:63], v[140:143], v[172:175], v[60:63]
	v_mfma_f32_16x16x32_bf16 v[56:59], v[148:151], v[172:175], v[56:59]
	v_mfma_f32_16x16x32_bf16 v[48:51], v[140:143], v[180:183], v[48:51]
	v_mfma_f32_16x16x32_bf16 v[40:43], v[148:151], v[180:183], v[40:43]
	v_mfma_f32_16x16x32_bf16 v[32:35], v[140:143], v[196:199], v[32:35]
	v_mfma_f32_16x16x32_bf16 v[24:27], v[148:151], v[196:199], v[24:27]
	v_mfma_f32_16x16x32_bf16 v[16:19], v[140:143], v[204:207], v[16:19]
	v_mfma_f32_16x16x32_bf16 v[8:11], v[148:151], v[204:207], v[8:11]
	v_mfma_f32_16x16x32_bf16 v[60:63], v[144:147], v[176:179], v[60:63]
	v_mfma_f32_16x16x32_bf16 v[56:59], v[152:155], v[176:179], v[56:59]
	v_mfma_f32_16x16x32_bf16 v[48:51], v[144:147], v[184:187], v[48:51]
	v_mfma_f32_16x16x32_bf16 v[40:43], v[152:155], v[184:187], v[40:43]
	v_mfma_f32_16x16x32_bf16 v[32:35], v[144:147], v[200:203], v[32:35]
	v_mfma_f32_16x16x32_bf16 v[24:27], v[152:155], v[200:203], v[24:27]
	v_mfma_f32_16x16x32_bf16 v[16:19], v[144:147], v[208:211], v[16:19]
	v_mfma_f32_16x16x32_bf16 v[8:11], v[152:155], v[208:211], v[8:11]
	v_mfma_f32_16x16x32_bf16 v[52:55], v[156:159], v[172:175], v[52:55]
	v_mfma_f32_16x16x32_bf16 v[44:47], v[164:167], v[172:175], v[44:47]
	v_mfma_f32_16x16x32_bf16 v[36:39], v[156:159], v[180:183], v[36:39]
	v_mfma_f32_16x16x32_bf16 v[28:31], v[164:167], v[180:183], v[28:31]
	v_mfma_f32_16x16x32_bf16 v[20:23], v[156:159], v[196:199], v[20:23]
	v_mfma_f32_16x16x32_bf16 v[12:15], v[164:167], v[196:199], v[12:15]
	v_mfma_f32_16x16x32_bf16 v[4:7], v[156:159], v[204:207], v[4:7]
	v_mfma_f32_16x16x32_bf16 v[0:3], v[164:167], v[204:207], v[0:3]
	v_mfma_f32_16x16x32_bf16 v[52:55], v[160:163], v[176:179], v[52:55]
	v_mfma_f32_16x16x32_bf16 v[44:47], v[168:171], v[176:179], v[44:47]
	v_mfma_f32_16x16x32_bf16 v[36:39], v[160:163], v[184:187], v[36:39]
	v_mfma_f32_16x16x32_bf16 v[28:31], v[168:171], v[184:187], v[28:31]
	v_mfma_f32_16x16x32_bf16 v[20:23], v[160:163], v[200:203], v[20:23]
	v_mfma_f32_16x16x32_bf16 v[12:15], v[168:171], v[200:203], v[12:15]
	v_mfma_f32_16x16x32_bf16 v[4:7], v[160:163], v[208:211], v[4:7]
	v_mfma_f32_16x16x32_bf16 v[0:3], v[168:171], v[208:211], v[0:3]
	s_barrier
	s_add_i32 s41, s41, 2
	s_add_u32 s18, s18, 0x100
	s_addc_u32 s19, s19, 0
	s_add_u32 s39, s39, 0x100
	s_addc_u32 s40, s40, 0
	s_cmp_gt_u32 s41, 61
	s_cbranch_scc0 .LBB0_1070
	s_and_b64 vcc, exec, s[6:7]
	s_cbranch_vccz .LBB0_1073
	s_barrier
